# v54: v41 minus the s_setprio 0/1 pair between the two MFMA runs of each phase and minus the repeated lgkmcnt(0) wait, all 7 GEMM K-loops
# speedup vs baseline: 1.0032x; 1.0032x over previous
.LBB0_374:
	ds_read_b128 v[152:155], v157
	ds_read_b128 v[160:163], v157 offset:1024
	ds_read_b128 v[164:167], v157 offset:2048
	ds_read_b128 v[168:171], v157 offset:3072
	ds_read_b128 v[172:175], v158
	ds_read_b128 v[176:179], v158 offset:1024
	ds_read_b128 v[180:183], v158 offset:2048
	ds_read_b128 v[184:187], v158 offset:3072
	s_add_u32 s28, s26, 0xfffc0080
	s_addc_u32 s29, s27, -1
	s_cmp_eq_u32 s80, 12
	s_cselect_b32 s31, s7, s29
	s_cselect_b32 s30, s21, s28
	s_cselect_b32 s29, s19, s59
	s_cselect_b32 s28, s57, s58
	v_lshl_add_u64 v[222:223], s[26:27], 0, v[144:145]
	s_add_i32 m0, s9, 0xc000
	ds_read_b128 v[188:191], v159
	ds_read_b128 v[192:195], v159 offset:1024
	ds_read_b128 v[196:199], v159 offset:2048
	ds_read_b128 v[200:203], v159 offset:3072
	ds_read_b128 v[204:207], v159 offset:4096
	ds_read_b128 v[210:213], v159 offset:5120
	ds_read_b128 v[214:217], v159 offset:6144
	ds_read_b128 v[218:221], v159 offset:7168
	global_load_lds_dwordx4 v[222:223], off
	v_lshl_add_u64 v[222:223], s[26:27], 0, v[146:147]
	s_add_i32 m0, s9, 0xe000
	s_nop 0
	global_load_lds_dwordx4 v[222:223], off
	s_waitcnt vmcnt(8)
	s_waitcnt lgkmcnt(0)
	s_barrier
	s_setprio 1
	v_mfma_f32_16x16x32_bf16 v[126:129], v[152:155], v[188:191], v[126:129]
	v_mfma_f32_16x16x32_bf16 v[122:125], v[164:167], v[188:191], v[122:125]
	v_mfma_f32_16x16x32_bf16 v[110:113], v[152:155], v[196:199], v[110:113]
	v_mfma_f32_16x16x32_bf16 v[106:109], v[164:167], v[196:199], v[106:109]
	v_mfma_f32_16x16x32_bf16 v[94:97], v[152:155], v[204:207], v[94:97]
	v_mfma_f32_16x16x32_bf16 v[90:93], v[164:167], v[204:207], v[90:93]
	v_mfma_f32_16x16x32_bf16 v[78:81], v[152:155], v[214:217], v[78:81]
	v_mfma_f32_16x16x32_bf16 v[74:77], v[164:167], v[214:217], v[74:77]
	v_mfma_f32_16x16x32_bf16 v[126:129], v[160:163], v[192:195], v[126:129]
	v_mfma_f32_16x16x32_bf16 v[122:125], v[168:171], v[192:195], v[122:125]
	v_mfma_f32_16x16x32_bf16 v[110:113], v[160:163], v[200:203], v[110:113]
	v_mfma_f32_16x16x32_bf16 v[106:109], v[168:171], v[200:203], v[106:109]
	v_mfma_f32_16x16x32_bf16 v[94:97], v[160:163], v[210:213], v[94:97]
	v_mfma_f32_16x16x32_bf16 v[90:93], v[168:171], v[210:213], v[90:93]
	v_mfma_f32_16x16x32_bf16 v[78:81], v[160:163], v[218:221], v[78:81]
	v_mfma_f32_16x16x32_bf16 v[74:77], v[168:171], v[218:221], v[74:77]
	v_mfma_f32_16x16x32_bf16 v[118:121], v[172:175], v[188:191], v[118:121]
	v_mfma_f32_16x16x32_bf16 v[114:117], v[180:183], v[188:191], v[114:117]
	v_mfma_f32_16x16x32_bf16 v[102:105], v[172:175], v[196:199], v[102:105]
	v_mfma_f32_16x16x32_bf16 v[98:101], v[180:183], v[196:199], v[98:101]
	v_mfma_f32_16x16x32_bf16 v[86:89], v[172:175], v[204:207], v[86:89]
	v_mfma_f32_16x16x32_bf16 v[82:85], v[180:183], v[204:207], v[82:85]
	v_mfma_f32_16x16x32_bf16 v[70:73], v[172:175], v[214:217], v[70:73]
	v_mfma_f32_16x16x32_bf16 v[66:69], v[180:183], v[214:217], v[66:69]
	v_mfma_f32_16x16x32_bf16 v[118:121], v[176:179], v[192:195], v[118:121]
	v_mfma_f32_16x16x32_bf16 v[114:117], v[184:187], v[192:195], v[114:117]
	v_mfma_f32_16x16x32_bf16 v[102:105], v[176:179], v[200:203], v[102:105]
	v_mfma_f32_16x16x32_bf16 v[98:101], v[184:187], v[200:203], v[98:101]
	v_mfma_f32_16x16x32_bf16 v[86:89], v[176:179], v[210:213], v[86:89]
	v_mfma_f32_16x16x32_bf16 v[82:85], v[184:187], v[210:213], v[82:85]
	v_mfma_f32_16x16x32_bf16 v[70:73], v[176:179], v[218:221], v[70:73]
	v_mfma_f32_16x16x32_bf16 v[66:69], v[184:187], v[218:221], v[66:69]
	s_setprio 0
	s_barrier
	s_add_i32 s81, s44, s35
	v_lshl_add_u64 v[222:223], s[28:29], 0, v[132:133]
	s_mov_b32 m0, s81
	ds_read_b128 v[188:191], v159 offset:16384
	ds_read_b128 v[192:195], v159 offset:17408
	ds_read_b128 v[196:199], v159 offset:18432
	ds_read_b128 v[200:203], v159 offset:19456
	ds_read_b128 v[204:207], v159 offset:20480
	ds_read_b128 v[210:213], v159 offset:21504
	ds_read_b128 v[214:217], v159 offset:22528
	ds_read_b128 v[218:221], v159 offset:23552
	global_load_lds_dwordx4 v[222:223], off
	s_add_i32 m0, s81, 0x2000
	s_add_u32 s82, s28, 0x40000
	v_lshl_add_u64 v[224:225], s[28:29], 0, v[136:137]
	s_addc_u32 s83, s29, 0
	s_add_i32 s81, s45, s35
	global_load_lds_dwordx4 v[224:225], off
	v_lshl_add_u64 v[226:227], s[82:83], 0, v[132:133]
	s_mov_b32 m0, s81
	v_lshl_add_u64 v[228:229], s[30:31], 0, v[134:135]
	global_load_lds_dwordx4 v[226:227], off
	v_lshl_add_u64 v[226:227], s[82:83], 0, v[136:137]
	s_add_i32 m0, s81, 0x2000
	s_nop 0
	global_load_lds_dwordx4 v[226:227], off
	v_lshl_add_u64 v[226:227], s[30:31], 0, v[130:131]
	s_mov_b32 m0, s9
	s_nop 0
	global_load_lds_dwordx4 v[226:227], off
	s_mov_b32 m0, s36
	s_nop 0
	global_load_lds_dwordx4 v[228:229], off
	s_waitcnt vmcnt(8)
	s_waitcnt lgkmcnt(0)
	s_barrier
	s_setprio 1
	v_mfma_f32_16x16x32_bf16 v[62:65], v[152:155], v[188:191], v[62:65]
	v_mfma_f32_16x16x32_bf16 v[58:61], v[164:167], v[188:191], v[58:61]
	v_mfma_f32_16x16x32_bf16 v[46:49], v[152:155], v[196:199], v[46:49]
	v_mfma_f32_16x16x32_bf16 v[42:45], v[164:167], v[196:199], v[42:45]
	v_mfma_f32_16x16x32_bf16 v[30:33], v[152:155], v[204:207], v[30:33]
	v_mfma_f32_16x16x32_bf16 v[26:29], v[164:167], v[204:207], v[26:29]
	v_mfma_f32_16x16x32_bf16 v[14:17], v[152:155], v[214:217], v[14:17]
	v_mfma_f32_16x16x32_bf16 v[10:13], v[164:167], v[214:217], v[10:13]
	v_mfma_f32_16x16x32_bf16 v[62:65], v[160:163], v[192:195], v[62:65]
	v_mfma_f32_16x16x32_bf16 v[58:61], v[168:171], v[192:195], v[58:61]
	v_mfma_f32_16x16x32_bf16 v[46:49], v[160:163], v[200:203], v[46:49]
	v_mfma_f32_16x16x32_bf16 v[42:45], v[168:171], v[200:203], v[42:45]
	v_mfma_f32_16x16x32_bf16 v[30:33], v[160:163], v[210:213], v[30:33]
	v_mfma_f32_16x16x32_bf16 v[26:29], v[168:171], v[210:213], v[26:29]
	v_mfma_f32_16x16x32_bf16 v[14:17], v[160:163], v[218:221], v[14:17]
	v_mfma_f32_16x16x32_bf16 v[10:13], v[168:171], v[218:221], v[10:13]
	v_mfma_f32_16x16x32_bf16 v[54:57], v[172:175], v[188:191], v[54:57]
	v_mfma_f32_16x16x32_bf16 v[50:53], v[180:183], v[188:191], v[50:53]
	v_mfma_f32_16x16x32_bf16 v[38:41], v[172:175], v[196:199], v[38:41]
	v_mfma_f32_16x16x32_bf16 v[34:37], v[180:183], v[196:199], v[34:37]
	v_mfma_f32_16x16x32_bf16 v[22:25], v[172:175], v[204:207], v[22:25]
	v_mfma_f32_16x16x32_bf16 v[18:21], v[180:183], v[204:207], v[18:21]
	v_mfma_f32_16x16x32_bf16 v[6:9], v[172:175], v[214:217], v[6:9]
	v_mfma_f32_16x16x32_bf16 v[2:5], v[180:183], v[214:217], v[2:5]
	v_mfma_f32_16x16x32_bf16 v[54:57], v[176:179], v[192:195], v[54:57]
	v_mfma_f32_16x16x32_bf16 v[50:53], v[184:187], v[192:195], v[50:53]
	v_mfma_f32_16x16x32_bf16 v[38:41], v[176:179], v[200:203], v[38:41]
	v_mfma_f32_16x16x32_bf16 v[34:37], v[184:187], v[200:203], v[34:37]
	v_mfma_f32_16x16x32_bf16 v[22:25], v[176:179], v[210:213], v[22:25]
	v_mfma_f32_16x16x32_bf16 v[18:21], v[184:187], v[210:213], v[18:21]
	v_mfma_f32_16x16x32_bf16 v[6:9], v[176:179], v[218:221], v[6:9]
	v_mfma_f32_16x16x32_bf16 v[2:5], v[184:187], v[218:221], v[2:5]
	s_setprio 0
	s_barrier
	s_add_i32 s81, 0, 0x18000
	v_add_u32_e32 v138, s81, v156
	s_add_i32 s82, 0, 0x1c000
	ds_read_b128 v[152:155], v138
	ds_read_b128 v[160:163], v138 offset:1024
	ds_read_b128 v[164:167], v138 offset:2048
	ds_read_b128 v[168:171], v138 offset:3072
	v_add_u32_e32 v138, 0x1000, v138
	ds_read_b128 v[172:175], v138
	ds_read_b128 v[176:179], v138 offset:1024
	ds_read_b128 v[180:183], v138 offset:2048
	ds_read_b128 v[184:187], v138 offset:3072
	s_add_u32 s30, s30, 0x40000
	s_addc_u32 s31, s31, 0
	s_mov_b32 m0, s37
	v_lshl_add_u64 v[230:231], s[30:31], 0, v[130:131]
	ds_read_b128 v[188:191], v159 offset:32768
	ds_read_b128 v[192:195], v159 offset:33792
	ds_read_b128 v[196:199], v159 offset:34816
	ds_read_b128 v[200:203], v159 offset:35840
	ds_read_b128 v[204:207], v159 offset:36864
	ds_read_b128 v[210:213], v159 offset:37888
	ds_read_b128 v[214:217], v159 offset:38912
	ds_read_b128 v[218:221], v159 offset:39936
	global_load_lds_dwordx4 v[230:231], off
	v_lshl_add_u64 v[230:231], s[30:31], 0, v[134:135]
	s_mov_b32 m0, s38
	s_nop 0
	global_load_lds_dwordx4 v[230:231], off
	s_waitcnt vmcnt(8)
	s_waitcnt lgkmcnt(0)
	s_barrier
	s_setprio 1
	v_mfma_f32_16x16x32_bf16 v[126:129], v[152:155], v[188:191], v[126:129]
	v_mfma_f32_16x16x32_bf16 v[122:125], v[164:167], v[188:191], v[122:125]
	v_mfma_f32_16x16x32_bf16 v[110:113], v[152:155], v[196:199], v[110:113]
	v_mfma_f32_16x16x32_bf16 v[106:109], v[164:167], v[196:199], v[106:109]
	v_mfma_f32_16x16x32_bf16 v[94:97], v[152:155], v[204:207], v[94:97]
	v_mfma_f32_16x16x32_bf16 v[90:93], v[164:167], v[204:207], v[90:93]
	v_mfma_f32_16x16x32_bf16 v[78:81], v[152:155], v[214:217], v[78:81]
	v_mfma_f32_16x16x32_bf16 v[74:77], v[164:167], v[214:217], v[74:77]
	v_mfma_f32_16x16x32_bf16 v[126:129], v[160:163], v[192:195], v[126:129]
	v_mfma_f32_16x16x32_bf16 v[122:125], v[168:171], v[192:195], v[122:125]
	v_mfma_f32_16x16x32_bf16 v[110:113], v[160:163], v[200:203], v[110:113]
	v_mfma_f32_16x16x32_bf16 v[106:109], v[168:171], v[200:203], v[106:109]
	v_mfma_f32_16x16x32_bf16 v[94:97], v[160:163], v[210:213], v[94:97]
	v_mfma_f32_16x16x32_bf16 v[90:93], v[168:171], v[210:213], v[90:93]
	v_mfma_f32_16x16x32_bf16 v[78:81], v[160:163], v[218:221], v[78:81]
	v_mfma_f32_16x16x32_bf16 v[74:77], v[168:171], v[218:221], v[74:77]
	v_mfma_f32_16x16x32_bf16 v[118:121], v[172:175], v[188:191], v[118:121]
	v_mfma_f32_16x16x32_bf16 v[114:117], v[180:183], v[188:191], v[114:117]
	v_mfma_f32_16x16x32_bf16 v[102:105], v[172:175], v[196:199], v[102:105]
	v_mfma_f32_16x16x32_bf16 v[98:101], v[180:183], v[196:199], v[98:101]
	v_mfma_f32_16x16x32_bf16 v[86:89], v[172:175], v[204:207], v[86:89]
	v_mfma_f32_16x16x32_bf16 v[82:85], v[180:183], v[204:207], v[82:85]
	v_mfma_f32_16x16x32_bf16 v[70:73], v[172:175], v[214:217], v[70:73]
	v_mfma_f32_16x16x32_bf16 v[66:69], v[180:183], v[214:217], v[66:69]
	v_mfma_f32_16x16x32_bf16 v[118:121], v[176:179], v[192:195], v[118:121]
	v_mfma_f32_16x16x32_bf16 v[114:117], v[184:187], v[192:195], v[114:117]
	v_mfma_f32_16x16x32_bf16 v[102:105], v[176:179], v[200:203], v[102:105]
	v_mfma_f32_16x16x32_bf16 v[98:101], v[184:187], v[200:203], v[98:101]
	v_mfma_f32_16x16x32_bf16 v[86:89], v[176:179], v[210:213], v[86:89]
	v_mfma_f32_16x16x32_bf16 v[82:85], v[184:187], v[210:213], v[82:85]
	v_mfma_f32_16x16x32_bf16 v[70:73], v[176:179], v[218:221], v[70:73]
	v_mfma_f32_16x16x32_bf16 v[66:69], v[184:187], v[218:221], v[66:69]
	s_setprio 0
	s_barrier
	s_add_i32 s30, s81, s35
	v_lshl_add_u64 v[222:223], v[222:223], 0, s[14:15]
	s_mov_b32 m0, s30
	ds_read_b128 v[188:191], v159 offset:49152
	ds_read_b128 v[192:195], v159 offset:50176
	ds_read_b128 v[196:199], v159 offset:51200
	ds_read_b128 v[200:203], v159 offset:52224
	ds_read_b128 v[204:207], v159 offset:53248
	ds_read_b128 v[210:213], v159 offset:54272
	ds_read_b128 v[214:217], v159 offset:55296
	ds_read_b128 v[218:221], v159 offset:56320
	global_load_lds_dwordx4 v[222:223], off
	s_add_i32 m0, s30, 0x2000
	s_add_u32 s28, s28, 0x40080
	v_lshl_add_u64 v[222:223], v[224:225], 0, s[14:15]
	s_addc_u32 s29, s29, 0
	s_add_i32 s30, s82, s35
	global_load_lds_dwordx4 v[222:223], off
	v_lshl_add_u64 v[222:223], s[28:29], 0, v[132:133]
	s_mov_b32 m0, s30
	s_nop 0
	global_load_lds_dwordx4 v[222:223], off
	v_lshl_add_u64 v[222:223], s[28:29], 0, v[136:137]
	s_add_i32 m0, s30, 0x2000
	s_nop 0
	global_load_lds_dwordx4 v[222:223], off
	v_lshl_add_u64 v[222:223], v[226:227], 0, s[14:15]
	s_mov_b32 m0, s40
	s_nop 0
	global_load_lds_dwordx4 v[222:223], off
	v_lshl_add_u64 v[222:223], v[228:229], 0, s[14:15]
	s_mov_b32 m0, s41
	s_nop 0
	global_load_lds_dwordx4 v[222:223], off
	s_waitcnt vmcnt(8)
	s_waitcnt lgkmcnt(0)
	s_barrier
	s_setprio 1
	v_mfma_f32_16x16x32_bf16 v[62:65], v[152:155], v[188:191], v[62:65]
	v_mfma_f32_16x16x32_bf16 v[58:61], v[164:167], v[188:191], v[58:61]
	v_mfma_f32_16x16x32_bf16 v[46:49], v[152:155], v[196:199], v[46:49]
	v_mfma_f32_16x16x32_bf16 v[42:45], v[164:167], v[196:199], v[42:45]
	v_mfma_f32_16x16x32_bf16 v[30:33], v[152:155], v[204:207], v[30:33]
	v_mfma_f32_16x16x32_bf16 v[26:29], v[164:167], v[204:207], v[26:29]
	v_mfma_f32_16x16x32_bf16 v[14:17], v[152:155], v[214:217], v[14:17]
	v_mfma_f32_16x16x32_bf16 v[10:13], v[164:167], v[214:217], v[10:13]
	v_mfma_f32_16x16x32_bf16 v[62:65], v[160:163], v[192:195], v[62:65]
	v_mfma_f32_16x16x32_bf16 v[58:61], v[168:171], v[192:195], v[58:61]
	v_mfma_f32_16x16x32_bf16 v[46:49], v[160:163], v[200:203], v[46:49]
	v_mfma_f32_16x16x32_bf16 v[42:45], v[168:171], v[200:203], v[42:45]
	v_mfma_f32_16x16x32_bf16 v[30:33], v[160:163], v[210:213], v[30:33]
	v_mfma_f32_16x16x32_bf16 v[26:29], v[168:171], v[210:213], v[26:29]
	v_mfma_f32_16x16x32_bf16 v[14:17], v[160:163], v[218:221], v[14:17]
	v_mfma_f32_16x16x32_bf16 v[10:13], v[168:171], v[218:221], v[10:13]
	v_mfma_f32_16x16x32_bf16 v[54:57], v[172:175], v[188:191], v[54:57]
	v_mfma_f32_16x16x32_bf16 v[50:53], v[180:183], v[188:191], v[50:53]
	v_mfma_f32_16x16x32_bf16 v[38:41], v[172:175], v[196:199], v[38:41]
	v_mfma_f32_16x16x32_bf16 v[34:37], v[180:183], v[196:199], v[34:37]
	v_mfma_f32_16x16x32_bf16 v[22:25], v[172:175], v[204:207], v[22:25]
	v_mfma_f32_16x16x32_bf16 v[18:21], v[180:183], v[204:207], v[18:21]
	v_mfma_f32_16x16x32_bf16 v[6:9], v[172:175], v[214:217], v[6:9]
	v_mfma_f32_16x16x32_bf16 v[2:5], v[180:183], v[214:217], v[2:5]
	v_mfma_f32_16x16x32_bf16 v[54:57], v[176:179], v[192:195], v[54:57]
	v_mfma_f32_16x16x32_bf16 v[50:53], v[184:187], v[192:195], v[50:53]
	v_mfma_f32_16x16x32_bf16 v[38:41], v[176:179], v[200:203], v[38:41]
	v_mfma_f32_16x16x32_bf16 v[34:37], v[184:187], v[200:203], v[34:37]
	v_mfma_f32_16x16x32_bf16 v[22:25], v[176:179], v[210:213], v[22:25]
	v_mfma_f32_16x16x32_bf16 v[18:21], v[184:187], v[210:213], v[18:21]
	v_mfma_f32_16x16x32_bf16 v[6:9], v[176:179], v[218:221], v[6:9]
	v_mfma_f32_16x16x32_bf16 v[2:5], v[184:187], v[218:221], v[2:5]
	s_setprio 0
	s_barrier
	s_add_i32 s80, s80, 2
	s_add_u32 s26, s26, 0x100
	s_addc_u32 s27, s27, 0
	s_add_u32 s58, s58, 0x100
	s_addc_u32 s59, s59, 0
	s_cmp_gt_u32 s80, 13
	s_cbranch_scc0 .LBB0_374
	s_and_b64 vcc, exec, s[16:17]
	s_cbranch_vccz .LBB0_377
	s_barrier

.LBB0_1381:
	ds_read_b128 v[130:133], v215
	ds_read_b128 v[134:137], v215 offset:1024
	ds_read_b128 v[138:141], v215 offset:2048
	ds_read_b128 v[142:145], v215 offset:3072
	ds_read_b128 v[146:149], v216
	ds_read_b128 v[150:153], v216 offset:1024
	ds_read_b128 v[154:157], v216 offset:2048
	ds_read_b128 v[158:161], v216 offset:3072
	s_add_u32 s30, s28, 0xfffc0080
	s_addc_u32 s31, s29, -1
	s_cmp_eq_u32 s66, 12
	s_cselect_b32 s35, s21, s31
	s_cselect_b32 s34, s27, s30
	s_cselect_b32 s31, s19, s65
	s_cselect_b32 s30, s63, s64
	v_lshl_add_u64 v[224:225], s[28:29], 0, v[188:189]
	s_add_i32 m0, s40, 0xc000
	ds_read_b128 v[162:165], v217
	ds_read_b128 v[166:169], v217 offset:1024
	ds_read_b128 v[170:173], v217 offset:2048
	ds_read_b128 v[174:177], v217 offset:3072
	ds_read_b128 v[196:199], v217 offset:4096
	ds_read_b128 v[200:203], v217 offset:5120
	ds_read_b128 v[204:207], v217 offset:6144
	ds_read_b128 v[220:223], v217 offset:7168
	global_load_lds_dwordx4 v[224:225], off
	v_lshl_add_u64 v[224:225], s[28:29], 0, v[190:191]
	s_add_i32 m0, s40, 0xe000
	s_nop 0
	global_load_lds_dwordx4 v[224:225], off
	s_waitcnt vmcnt(8)
	s_waitcnt lgkmcnt(0)
	s_barrier
	s_setprio 1
	v_mfma_f32_16x16x32_bf16 v[126:129], v[130:133], v[162:165], v[126:129]
	v_mfma_f32_16x16x32_bf16 v[122:125], v[138:141], v[162:165], v[122:125]
	v_mfma_f32_16x16x32_bf16 v[110:113], v[130:133], v[170:173], v[110:113]
	v_mfma_f32_16x16x32_bf16 v[106:109], v[138:141], v[170:173], v[106:109]
	v_mfma_f32_16x16x32_bf16 v[94:97], v[130:133], v[196:199], v[94:97]
	v_mfma_f32_16x16x32_bf16 v[90:93], v[138:141], v[196:199], v[90:93]
	v_mfma_f32_16x16x32_bf16 v[78:81], v[130:133], v[204:207], v[78:81]
	v_mfma_f32_16x16x32_bf16 v[74:77], v[138:141], v[204:207], v[74:77]
	v_mfma_f32_16x16x32_bf16 v[126:129], v[134:137], v[166:169], v[126:129]
	v_mfma_f32_16x16x32_bf16 v[122:125], v[142:145], v[166:169], v[122:125]
	v_mfma_f32_16x16x32_bf16 v[110:113], v[134:137], v[174:177], v[110:113]
	v_mfma_f32_16x16x32_bf16 v[106:109], v[142:145], v[174:177], v[106:109]
	v_mfma_f32_16x16x32_bf16 v[94:97], v[134:137], v[200:203], v[94:97]
	v_mfma_f32_16x16x32_bf16 v[90:93], v[142:145], v[200:203], v[90:93]
	v_mfma_f32_16x16x32_bf16 v[78:81], v[134:137], v[220:223], v[78:81]
	v_mfma_f32_16x16x32_bf16 v[74:77], v[142:145], v[220:223], v[74:77]
	v_mfma_f32_16x16x32_bf16 v[118:121], v[146:149], v[162:165], v[118:121]
	v_mfma_f32_16x16x32_bf16 v[114:117], v[154:157], v[162:165], v[114:117]
	v_mfma_f32_16x16x32_bf16 v[102:105], v[146:149], v[170:173], v[102:105]
	v_mfma_f32_16x16x32_bf16 v[98:101], v[154:157], v[170:173], v[98:101]
	v_mfma_f32_16x16x32_bf16 v[86:89], v[146:149], v[196:199], v[86:89]
	v_mfma_f32_16x16x32_bf16 v[82:85], v[154:157], v[196:199], v[82:85]
	v_mfma_f32_16x16x32_bf16 v[70:73], v[146:149], v[204:207], v[70:73]
	v_mfma_f32_16x16x32_bf16 v[66:69], v[154:157], v[204:207], v[66:69]
	v_mfma_f32_16x16x32_bf16 v[118:121], v[150:153], v[166:169], v[118:121]
	v_mfma_f32_16x16x32_bf16 v[114:117], v[158:161], v[166:169], v[114:117]
	v_mfma_f32_16x16x32_bf16 v[102:105], v[150:153], v[174:177], v[102:105]
	v_mfma_f32_16x16x32_bf16 v[98:101], v[158:161], v[174:177], v[98:101]
	v_mfma_f32_16x16x32_bf16 v[86:89], v[150:153], v[200:203], v[86:89]
	v_mfma_f32_16x16x32_bf16 v[82:85], v[158:161], v[200:203], v[82:85]
	v_mfma_f32_16x16x32_bf16 v[70:73], v[150:153], v[220:223], v[70:73]
	v_mfma_f32_16x16x32_bf16 v[66:69], v[158:161], v[220:223], v[66:69]
	s_setprio 0
	s_barrier
	s_add_i32 s67, s56, s39
	v_lshl_add_u64 v[224:225], s[30:31], 0, v[182:183]
	s_mov_b32 m0, s67
	ds_read_b128 v[162:165], v217 offset:16384
	ds_read_b128 v[166:169], v217 offset:17408
	ds_read_b128 v[170:173], v217 offset:18432
	ds_read_b128 v[174:177], v217 offset:19456
	ds_read_b128 v[196:199], v217 offset:20480
	ds_read_b128 v[200:203], v217 offset:21504
	ds_read_b128 v[204:207], v217 offset:22528
	ds_read_b128 v[220:223], v217 offset:23552
	global_load_lds_dwordx4 v[224:225], off
	s_add_i32 m0, s67, 0x2000
	s_add_u32 s68, s30, 0x40000
	v_lshl_add_u64 v[226:227], s[30:31], 0, v[186:187]
	s_addc_u32 s69, s31, 0
	s_add_i32 s67, s57, s39
	global_load_lds_dwordx4 v[226:227], off
	v_lshl_add_u64 v[228:229], s[68:69], 0, v[182:183]
	s_mov_b32 m0, s67
	v_lshl_add_u64 v[230:231], s[34:35], 0, v[184:185]
	global_load_lds_dwordx4 v[228:229], off
	v_lshl_add_u64 v[228:229], s[68:69], 0, v[186:187]
	s_add_i32 m0, s67, 0x2000
	s_nop 0
	global_load_lds_dwordx4 v[228:229], off
	v_lshl_add_u64 v[228:229], s[34:35], 0, v[180:181]
	s_mov_b32 m0, s40
	s_nop 0
	global_load_lds_dwordx4 v[228:229], off
	s_mov_b32 m0, s41
	s_nop 0
	global_load_lds_dwordx4 v[230:231], off
	s_waitcnt vmcnt(8)
	s_waitcnt lgkmcnt(0)
	s_barrier
	s_setprio 1
	v_mfma_f32_16x16x32_bf16 v[62:65], v[130:133], v[162:165], v[62:65]
	v_mfma_f32_16x16x32_bf16 v[58:61], v[138:141], v[162:165], v[58:61]
	v_mfma_f32_16x16x32_bf16 v[46:49], v[130:133], v[170:173], v[46:49]
	v_mfma_f32_16x16x32_bf16 v[42:45], v[138:141], v[170:173], v[42:45]
	v_mfma_f32_16x16x32_bf16 v[30:33], v[130:133], v[196:199], v[30:33]
	v_mfma_f32_16x16x32_bf16 v[26:29], v[138:141], v[196:199], v[26:29]
	v_mfma_f32_16x16x32_bf16 v[14:17], v[130:133], v[204:207], v[14:17]
	v_mfma_f32_16x16x32_bf16 v[10:13], v[138:141], v[204:207], v[10:13]
	v_mfma_f32_16x16x32_bf16 v[62:65], v[134:137], v[166:169], v[62:65]
	v_mfma_f32_16x16x32_bf16 v[58:61], v[142:145], v[166:169], v[58:61]
	v_mfma_f32_16x16x32_bf16 v[46:49], v[134:137], v[174:177], v[46:49]
	v_mfma_f32_16x16x32_bf16 v[42:45], v[142:145], v[174:177], v[42:45]
	v_mfma_f32_16x16x32_bf16 v[30:33], v[134:137], v[200:203], v[30:33]
	v_mfma_f32_16x16x32_bf16 v[26:29], v[142:145], v[200:203], v[26:29]
	v_mfma_f32_16x16x32_bf16 v[14:17], v[134:137], v[220:223], v[14:17]
	v_mfma_f32_16x16x32_bf16 v[10:13], v[142:145], v[220:223], v[10:13]
	v_mfma_f32_16x16x32_bf16 v[54:57], v[146:149], v[162:165], v[54:57]
	v_mfma_f32_16x16x32_bf16 v[50:53], v[154:157], v[162:165], v[50:53]
	v_mfma_f32_16x16x32_bf16 v[38:41], v[146:149], v[170:173], v[38:41]
	v_mfma_f32_16x16x32_bf16 v[34:37], v[154:157], v[170:173], v[34:37]
	v_mfma_f32_16x16x32_bf16 v[22:25], v[146:149], v[196:199], v[22:25]
	v_mfma_f32_16x16x32_bf16 v[18:21], v[154:157], v[196:199], v[18:21]
	v_mfma_f32_16x16x32_bf16 v[6:9], v[146:149], v[204:207], v[6:9]
	v_mfma_f32_16x16x32_bf16 v[2:5], v[154:157], v[204:207], v[2:5]
	v_mfma_f32_16x16x32_bf16 v[54:57], v[150:153], v[166:169], v[54:57]
	v_mfma_f32_16x16x32_bf16 v[50:53], v[158:161], v[166:169], v[50:53]
	v_mfma_f32_16x16x32_bf16 v[38:41], v[150:153], v[174:177], v[38:41]
	v_mfma_f32_16x16x32_bf16 v[34:37], v[158:161], v[174:177], v[34:37]
	v_mfma_f32_16x16x32_bf16 v[22:25], v[150:153], v[200:203], v[22:25]
	v_mfma_f32_16x16x32_bf16 v[18:21], v[158:161], v[200:203], v[18:21]
	v_mfma_f32_16x16x32_bf16 v[6:9], v[150:153], v[220:223], v[6:9]
	v_mfma_f32_16x16x32_bf16 v[2:5], v[158:161], v[220:223], v[2:5]
	s_setprio 0
	s_barrier
	s_add_i32 s67, 0, 0x18000
	s_add_i32 s68, 0, 0x1c000
	v_add_u32_e32 v142, s67, v213
	v_add_u32_e32 v158, s68, v213
	ds_read_b128 v[130:133], v142
	ds_read_b128 v[134:137], v142 offset:1024
	ds_read_b128 v[138:141], v142 offset:2048
	ds_read_b128 v[142:145], v142 offset:3072
	ds_read_b128 v[146:149], v158
	ds_read_b128 v[150:153], v158 offset:1024
	ds_read_b128 v[154:157], v158 offset:2048
	ds_read_b128 v[158:161], v158 offset:3072
	s_add_u32 s34, s34, 0x40000
	s_addc_u32 s35, s35, 0
	s_mov_b32 m0, s42
	v_lshl_add_u64 v[232:233], s[34:35], 0, v[180:181]
	ds_read_b128 v[162:165], v217 offset:32768
	ds_read_b128 v[166:169], v217 offset:33792
	ds_read_b128 v[170:173], v217 offset:34816
	ds_read_b128 v[174:177], v217 offset:35840
	ds_read_b128 v[196:199], v217 offset:36864
	ds_read_b128 v[200:203], v217 offset:37888
	ds_read_b128 v[204:207], v217 offset:38912
	ds_read_b128 v[220:223], v217 offset:39936
	global_load_lds_dwordx4 v[232:233], off
	v_lshl_add_u64 v[232:233], s[34:35], 0, v[184:185]
	s_mov_b32 m0, s43
	s_nop 0
	global_load_lds_dwordx4 v[232:233], off
	s_waitcnt vmcnt(8)
	s_waitcnt lgkmcnt(0)
	s_barrier
	s_setprio 1
	v_mfma_f32_16x16x32_bf16 v[126:129], v[130:133], v[162:165], v[126:129]
	v_mfma_f32_16x16x32_bf16 v[122:125], v[138:141], v[162:165], v[122:125]
	v_mfma_f32_16x16x32_bf16 v[110:113], v[130:133], v[170:173], v[110:113]
	v_mfma_f32_16x16x32_bf16 v[106:109], v[138:141], v[170:173], v[106:109]
	v_mfma_f32_16x16x32_bf16 v[94:97], v[130:133], v[196:199], v[94:97]
	v_mfma_f32_16x16x32_bf16 v[90:93], v[138:141], v[196:199], v[90:93]
	v_mfma_f32_16x16x32_bf16 v[78:81], v[130:133], v[204:207], v[78:81]
	v_mfma_f32_16x16x32_bf16 v[74:77], v[138:141], v[204:207], v[74:77]
	v_mfma_f32_16x16x32_bf16 v[126:129], v[134:137], v[166:169], v[126:129]
	v_mfma_f32_16x16x32_bf16 v[122:125], v[142:145], v[166:169], v[122:125]
	v_mfma_f32_16x16x32_bf16 v[110:113], v[134:137], v[174:177], v[110:113]
	v_mfma_f32_16x16x32_bf16 v[106:109], v[142:145], v[174:177], v[106:109]
	v_mfma_f32_16x16x32_bf16 v[94:97], v[134:137], v[200:203], v[94:97]
	v_mfma_f32_16x16x32_bf16 v[90:93], v[142:145], v[200:203], v[90:93]
	v_mfma_f32_16x16x32_bf16 v[78:81], v[134:137], v[220:223], v[78:81]
	v_mfma_f32_16x16x32_bf16 v[74:77], v[142:145], v[220:223], v[74:77]
	v_mfma_f32_16x16x32_bf16 v[118:121], v[146:149], v[162:165], v[118:121]
	v_mfma_f32_16x16x32_bf16 v[114:117], v[154:157], v[162:165], v[114:117]
	v_mfma_f32_16x16x32_bf16 v[102:105], v[146:149], v[170:173], v[102:105]
	v_mfma_f32_16x16x32_bf16 v[98:101], v[154:157], v[170:173], v[98:101]
	v_mfma_f32_16x16x32_bf16 v[86:89], v[146:149], v[196:199], v[86:89]
	v_mfma_f32_16x16x32_bf16 v[82:85], v[154:157], v[196:199], v[82:85]
	v_mfma_f32_16x16x32_bf16 v[70:73], v[146:149], v[204:207], v[70:73]
	v_mfma_f32_16x16x32_bf16 v[66:69], v[154:157], v[204:207], v[66:69]
	v_mfma_f32_16x16x32_bf16 v[118:121], v[150:153], v[166:169], v[118:121]
	v_mfma_f32_16x16x32_bf16 v[114:117], v[158:161], v[166:169], v[114:117]
	v_mfma_f32_16x16x32_bf16 v[102:105], v[150:153], v[174:177], v[102:105]
	v_mfma_f32_16x16x32_bf16 v[98:101], v[158:161], v[174:177], v[98:101]
	v_mfma_f32_16x16x32_bf16 v[86:89], v[150:153], v[200:203], v[86:89]
	v_mfma_f32_16x16x32_bf16 v[82:85], v[158:161], v[200:203], v[82:85]
	v_mfma_f32_16x16x32_bf16 v[70:73], v[150:153], v[220:223], v[70:73]
	v_mfma_f32_16x16x32_bf16 v[66:69], v[158:161], v[220:223], v[66:69]
	s_setprio 0
	s_barrier
	s_add_i32 s34, s67, s39
	v_lshl_add_u64 v[224:225], v[224:225], 0, s[14:15]
	s_mov_b32 m0, s34
	ds_read_b128 v[162:165], v217 offset:49152
	ds_read_b128 v[166:169], v217 offset:50176
	ds_read_b128 v[170:173], v217 offset:51200
	ds_read_b128 v[174:177], v217 offset:52224
	ds_read_b128 v[196:199], v217 offset:53248
	ds_read_b128 v[200:203], v217 offset:54272
	ds_read_b128 v[204:207], v217 offset:55296
	ds_read_b128 v[220:223], v217 offset:56320
	global_load_lds_dwordx4 v[224:225], off
	s_add_i32 m0, s34, 0x2000
	s_add_u32 s30, s30, 0x40080
	v_lshl_add_u64 v[224:225], v[226:227], 0, s[14:15]
	s_addc_u32 s31, s31, 0
	s_add_i32 s34, s68, s39
	global_load_lds_dwordx4 v[224:225], off
	v_lshl_add_u64 v[224:225], s[30:31], 0, v[182:183]
	s_mov_b32 m0, s34
	s_nop 0
	global_load_lds_dwordx4 v[224:225], off
	v_lshl_add_u64 v[224:225], s[30:31], 0, v[186:187]
	s_add_i32 m0, s34, 0x2000
	s_nop 0
	global_load_lds_dwordx4 v[224:225], off
	v_lshl_add_u64 v[224:225], v[228:229], 0, s[14:15]
	s_mov_b32 m0, s52
	s_nop 0
	global_load_lds_dwordx4 v[224:225], off
	v_lshl_add_u64 v[224:225], v[230:231], 0, s[14:15]
	s_mov_b32 m0, s53
	s_nop 0
	global_load_lds_dwordx4 v[224:225], off
	s_waitcnt vmcnt(8)
	s_waitcnt lgkmcnt(0)
	s_barrier
	s_setprio 1
	v_mfma_f32_16x16x32_bf16 v[62:65], v[130:133], v[162:165], v[62:65]
	v_mfma_f32_16x16x32_bf16 v[58:61], v[138:141], v[162:165], v[58:61]
	v_mfma_f32_16x16x32_bf16 v[46:49], v[130:133], v[170:173], v[46:49]
	v_mfma_f32_16x16x32_bf16 v[42:45], v[138:141], v[170:173], v[42:45]
	v_mfma_f32_16x16x32_bf16 v[30:33], v[130:133], v[196:199], v[30:33]
	v_mfma_f32_16x16x32_bf16 v[26:29], v[138:141], v[196:199], v[26:29]
	v_mfma_f32_16x16x32_bf16 v[14:17], v[130:133], v[204:207], v[14:17]
	v_mfma_f32_16x16x32_bf16 v[10:13], v[138:141], v[204:207], v[10:13]
	v_mfma_f32_16x16x32_bf16 v[62:65], v[134:137], v[166:169], v[62:65]
	v_mfma_f32_16x16x32_bf16 v[58:61], v[142:145], v[166:169], v[58:61]
	v_mfma_f32_16x16x32_bf16 v[46:49], v[134:137], v[174:177], v[46:49]
	v_mfma_f32_16x16x32_bf16 v[42:45], v[142:145], v[174:177], v[42:45]
	v_mfma_f32_16x16x32_bf16 v[30:33], v[134:137], v[200:203], v[30:33]
	v_mfma_f32_16x16x32_bf16 v[26:29], v[142:145], v[200:203], v[26:29]
	v_mfma_f32_16x16x32_bf16 v[14:17], v[134:137], v[220:223], v[14:17]
	v_mfma_f32_16x16x32_bf16 v[10:13], v[142:145], v[220:223], v[10:13]
	v_mfma_f32_16x16x32_bf16 v[54:57], v[146:149], v[162:165], v[54:57]
	v_mfma_f32_16x16x32_bf16 v[50:53], v[154:157], v[162:165], v[50:53]
	v_mfma_f32_16x16x32_bf16 v[38:41], v[146:149], v[170:173], v[38:41]
	v_mfma_f32_16x16x32_bf16 v[34:37], v[154:157], v[170:173], v[34:37]
	v_mfma_f32_16x16x32_bf16 v[22:25], v[146:149], v[196:199], v[22:25]
	v_mfma_f32_16x16x32_bf16 v[18:21], v[154:157], v[196:199], v[18:21]
	v_mfma_f32_16x16x32_bf16 v[6:9], v[146:149], v[204:207], v[6:9]
	v_mfma_f32_16x16x32_bf16 v[2:5], v[154:157], v[204:207], v[2:5]
	v_mfma_f32_16x16x32_bf16 v[54:57], v[150:153], v[166:169], v[54:57]
	v_mfma_f32_16x16x32_bf16 v[50:53], v[158:161], v[166:169], v[50:53]
	v_mfma_f32_16x16x32_bf16 v[38:41], v[150:153], v[174:177], v[38:41]
	v_mfma_f32_16x16x32_bf16 v[34:37], v[158:161], v[174:177], v[34:37]
	v_mfma_f32_16x16x32_bf16 v[22:25], v[150:153], v[200:203], v[22:25]
	v_mfma_f32_16x16x32_bf16 v[18:21], v[158:161], v[200:203], v[18:21]
	v_mfma_f32_16x16x32_bf16 v[6:9], v[150:153], v[220:223], v[6:9]
	v_mfma_f32_16x16x32_bf16 v[2:5], v[158:161], v[220:223], v[2:5]
	s_setprio 0
	s_barrier
	s_add_i32 s66, s66, 2
	s_add_u32 s28, s28, 0x100
	s_addc_u32 s29, s29, 0
	s_add_u32 s64, s64, 0x100
	s_addc_u32 s65, s65, 0
	s_cmp_gt_u32 s66, 13
	s_cbranch_scc0 .LBB0_1381
	s_and_b64 vcc, exec, s[16:17]
	s_cbranch_vccz .LBB0_1384
	s_barrier

.LBB0_1416:
	ds_read_b128 v[2:5], v135
	ds_read_b128 v[6:9], v135 offset:1024
	ds_read_b128 v[10:13], v135 offset:2048
	ds_read_b128 v[14:17], v135 offset:3072
	ds_read_b128 v[18:21], v136
	ds_read_b128 v[22:25], v136 offset:1024
	ds_read_b128 v[26:29], v136 offset:2048
	ds_read_b128 v[30:33], v136 offset:3072
	s_add_u32 s30, s30, 0x40080
	s_addc_u32 s31, s31, 0
	s_mov_b32 m0, s44
	v_lshl_add_u64 v[66:67], s[30:31], 0, v[180:181]
	ds_read_b128 v[34:37], v137
	ds_read_b128 v[38:41], v137 offset:1024
	ds_read_b128 v[42:45], v137 offset:2048
	ds_read_b128 v[46:49], v137 offset:3072
	ds_read_b128 v[50:53], v137 offset:4096
	ds_read_b128 v[54:57], v137 offset:5120
	ds_read_b128 v[58:61], v137 offset:6144
	ds_read_b128 v[62:65], v137 offset:7168
	global_load_lds_dwordx4 v[66:67], off
	v_lshl_add_u64 v[66:67], s[30:31], 0, v[184:185]
	s_mov_b32 m0, s45
	s_nop 0
	global_load_lds_dwordx4 v[66:67], off
	s_waitcnt vmcnt(8)
	s_waitcnt lgkmcnt(0)
	s_barrier
	s_setprio 1
	v_mfma_f32_16x16x32_bf16 v[90:93], v[2:5], v[58:61], 0
	v_mfma_f32_16x16x32_bf16 v[66:69], v[2:5], v[34:37], 0
	v_mfma_f32_16x16x32_bf16 v[70:73], v[10:13], v[34:37], 0
	v_mfma_f32_16x16x32_bf16 v[74:77], v[2:5], v[42:45], 0
	v_mfma_f32_16x16x32_bf16 v[78:81], v[10:13], v[42:45], 0
	v_mfma_f32_16x16x32_bf16 v[82:85], v[2:5], v[50:53], 0
	v_mfma_f32_16x16x32_bf16 v[86:89], v[10:13], v[50:53], 0
	v_mfma_f32_16x16x32_bf16 v[94:97], v[6:9], v[62:65], v[90:93]
	v_mfma_f32_16x16x32_bf16 v[90:93], v[10:13], v[58:61], 0
	v_mfma_f32_16x16x32_bf16 v[66:69], v[6:9], v[38:41], v[66:69]
	v_mfma_f32_16x16x32_bf16 v[70:73], v[14:17], v[38:41], v[70:73]
	v_mfma_f32_16x16x32_bf16 v[74:77], v[6:9], v[46:49], v[74:77]
	v_mfma_f32_16x16x32_bf16 v[78:81], v[14:17], v[46:49], v[78:81]
	v_mfma_f32_16x16x32_bf16 v[82:85], v[6:9], v[54:57], v[82:85]
	v_mfma_f32_16x16x32_bf16 v[86:89], v[14:17], v[54:57], v[86:89]
	v_mfma_f32_16x16x32_bf16 v[102:105], v[14:17], v[62:65], v[90:93]
	v_mfma_f32_16x16x32_bf16 v[90:93], v[18:21], v[34:37], 0
	v_mfma_f32_16x16x32_bf16 v[34:37], v[26:29], v[34:37], 0
	v_mfma_f32_16x16x32_bf16 v[110:113], v[22:25], v[38:41], v[90:93]
	v_mfma_f32_16x16x32_bf16 v[34:37], v[30:33], v[38:41], v[34:37]
	v_mfma_f32_16x16x32_bf16 v[38:41], v[18:21], v[42:45], 0
	v_mfma_f32_16x16x32_bf16 v[42:45], v[26:29], v[42:45], 0
	v_mfma_f32_16x16x32_bf16 v[38:41], v[22:25], v[46:49], v[38:41]
	v_mfma_f32_16x16x32_bf16 v[42:45], v[30:33], v[46:49], v[42:45]
	v_mfma_f32_16x16x32_bf16 v[46:49], v[18:21], v[50:53], 0
	v_mfma_f32_16x16x32_bf16 v[50:53], v[26:29], v[50:53], 0
	v_mfma_f32_16x16x32_bf16 v[46:49], v[22:25], v[54:57], v[46:49]
	v_mfma_f32_16x16x32_bf16 v[54:57], v[30:33], v[54:57], v[50:53]
	v_mfma_f32_16x16x32_bf16 v[50:53], v[18:21], v[58:61], 0
	v_mfma_f32_16x16x32_bf16 v[138:141], v[22:25], v[62:65], v[50:53]
	v_mfma_f32_16x16x32_bf16 v[50:53], v[26:29], v[58:61], 0
	v_mfma_f32_16x16x32_bf16 v[142:145], v[30:33], v[62:65], v[50:53]
	s_setprio 0
	s_barrier
	s_mov_b32 m0, s48
	v_lshl_add_u64 v[130:131], s[4:5], 0, v[182:183]
	s_add_u32 s30, s4, 0x40000
	s_nop 1
	ds_read_b128 v[50:53], v137 offset:16384
	ds_read_b128 v[58:61], v137 offset:17408
	ds_read_b128 v[62:65], v137 offset:18432
	ds_read_b128 v[90:93], v137 offset:19456
	ds_read_b128 v[98:101], v137 offset:20480
	ds_read_b128 v[106:109], v137 offset:21504
	ds_read_b128 v[114:117], v137 offset:22528
	ds_read_b128 v[118:121], v137 offset:23552
	global_load_lds_dwordx4 v[130:131], off
	v_lshl_add_u64 v[250:251], s[4:5], 0, v[186:187]
	s_mov_b32 m0, s49
	s_addc_u32 s31, s5, 0
	global_load_lds_dwordx4 v[250:251], off
	v_lshl_add_u64 v[122:123], s[30:31], 0, v[182:183]
	s_mov_b32 m0, s52
	v_lshl_add_u64 v[252:253], s[22:23], 0, v[180:181]
	global_load_lds_dwordx4 v[122:123], off
	v_lshl_add_u64 v[122:123], s[30:31], 0, v[186:187]
	s_mov_b32 m0, s53
	v_lshl_add_u64 v[208:209], s[22:23], 0, v[184:185]
	global_load_lds_dwordx4 v[122:123], off
	s_mov_b32 m0, s25
	s_nop 0
	global_load_lds_dwordx4 v[252:253], off
	s_mov_b32 m0, s27
	s_nop 0
	global_load_lds_dwordx4 v[208:209], off
	s_waitcnt vmcnt(8)
	s_waitcnt lgkmcnt(0)
	s_barrier
	s_setprio 1
	v_mfma_f32_16x16x32_bf16 v[122:125], v[2:5], v[50:53], 0
	v_mfma_f32_16x16x32_bf16 v[146:149], v[6:9], v[58:61], v[122:125]
	v_mfma_f32_16x16x32_bf16 v[122:125], v[10:13], v[50:53], 0
	v_mfma_f32_16x16x32_bf16 v[150:153], v[14:17], v[58:61], v[122:125]
	v_mfma_f32_16x16x32_bf16 v[122:125], v[2:5], v[62:65], 0
	v_mfma_f32_16x16x32_bf16 v[154:157], v[6:9], v[90:93], v[122:125]
	v_mfma_f32_16x16x32_bf16 v[122:125], v[10:13], v[62:65], 0
	v_mfma_f32_16x16x32_bf16 v[158:161], v[14:17], v[90:93], v[122:125]
	v_mfma_f32_16x16x32_bf16 v[122:125], v[2:5], v[98:101], 0
	v_mfma_f32_16x16x32_bf16 v[2:5], v[2:5], v[114:117], 0
	v_mfma_f32_16x16x32_bf16 v[162:165], v[6:9], v[106:109], v[122:125]
	v_mfma_f32_16x16x32_bf16 v[2:5], v[6:9], v[118:121], v[2:5]
	v_mfma_f32_16x16x32_bf16 v[6:9], v[10:13], v[114:117], 0
	v_mfma_f32_16x16x32_bf16 v[122:125], v[10:13], v[98:101], 0
	v_mfma_f32_16x16x32_bf16 v[6:9], v[14:17], v[118:121], v[6:9]
	v_mfma_f32_16x16x32_bf16 v[166:169], v[14:17], v[106:109], v[122:125]
	v_mfma_f32_16x16x32_bf16 v[10:13], v[18:21], v[50:53], 0
	v_mfma_f32_16x16x32_bf16 v[14:17], v[22:25], v[58:61], v[10:13]
	v_mfma_f32_16x16x32_bf16 v[10:13], v[26:29], v[50:53], 0
	v_mfma_f32_16x16x32_bf16 v[170:173], v[30:33], v[58:61], v[10:13]
	v_mfma_f32_16x16x32_bf16 v[10:13], v[18:21], v[62:65], 0
	v_mfma_f32_16x16x32_bf16 v[174:177], v[22:25], v[90:93], v[10:13]
	v_mfma_f32_16x16x32_bf16 v[10:13], v[26:29], v[62:65], 0
	v_mfma_f32_16x16x32_bf16 v[188:191], v[30:33], v[90:93], v[10:13]
	v_mfma_f32_16x16x32_bf16 v[10:13], v[18:21], v[98:101], 0
	v_mfma_f32_16x16x32_bf16 v[192:195], v[22:25], v[106:109], v[10:13]
	v_mfma_f32_16x16x32_bf16 v[10:13], v[26:29], v[98:101], 0
	v_mfma_f32_16x16x32_bf16 v[196:199], v[30:33], v[106:109], v[10:13]
	v_mfma_f32_16x16x32_bf16 v[10:13], v[18:21], v[114:117], 0
	v_mfma_f32_16x16x32_bf16 v[200:203], v[22:25], v[118:121], v[10:13]
	v_mfma_f32_16x16x32_bf16 v[10:13], v[26:29], v[114:117], 0
	v_mfma_f32_16x16x32_bf16 v[204:207], v[30:33], v[118:121], v[10:13]
	s_setprio 0
	s_barrier
	s_add_i32 s17, 0, 0x18000
	v_add_u32_e32 v18, s17, v133
	s_add_i32 s19, 0, 0x1c000
	s_nop 1
	ds_read_b128 v[10:13], v18
	ds_read_b128 v[22:25], v18 offset:1024
	ds_read_b128 v[30:33], v18 offset:2048
	ds_read_b128 v[210:213], v18 offset:3072
	v_add_u32_e32 v18, s19, v133
	ds_read_b128 v[214:217], v18
	ds_read_b128 v[218:221], v18 offset:1024
	ds_read_b128 v[222:225], v18 offset:2048
	ds_read_b128 v[226:229], v18 offset:3072
	s_add_u32 s30, s22, 0x40000
	s_addc_u32 s31, s23, 0
	s_mov_b32 m0, s29
	v_lshl_add_u64 v[50:51], s[30:31], 0, v[180:181]
	ds_read_b128 v[18:21], v137 offset:32768
	ds_read_b128 v[26:29], v137 offset:33792
	ds_read_b128 v[62:65], v137 offset:34816
	ds_read_b128 v[230:233], v137 offset:35840
	ds_read_b128 v[234:237], v137 offset:36864
	ds_read_b128 v[238:241], v137 offset:37888
	ds_read_b128 v[242:245], v137 offset:38912
	ds_read_b128 v[246:249], v137 offset:39936
	global_load_lds_dwordx4 v[50:51], off
	v_lshl_add_u64 v[50:51], s[30:31], 0, v[184:185]
	s_mov_b32 m0, s35
	s_nop 0
	global_load_lds_dwordx4 v[50:51], off
	s_waitcnt vmcnt(8)
	s_waitcnt lgkmcnt(0)
	s_barrier
	s_setprio 1
	v_mfma_f32_16x16x32_bf16 v[50:53], v[10:13], v[18:21], v[66:69]
	v_mfma_f32_16x16x32_bf16 v[122:125], v[22:25], v[26:29], v[50:53]
	v_mfma_f32_16x16x32_bf16 v[50:53], v[30:33], v[18:21], v[70:73]
	v_mfma_f32_16x16x32_bf16 v[114:117], v[210:213], v[26:29], v[50:53]
	v_mfma_f32_16x16x32_bf16 v[50:53], v[10:13], v[62:65], v[74:77]
	v_mfma_f32_16x16x32_bf16 v[106:109], v[22:25], v[230:233], v[50:53]
	v_mfma_f32_16x16x32_bf16 v[50:53], v[30:33], v[62:65], v[78:81]
	v_mfma_f32_16x16x32_bf16 v[98:101], v[210:213], v[230:233], v[50:53]
	v_mfma_f32_16x16x32_bf16 v[50:53], v[10:13], v[234:237], v[82:85]
	v_mfma_f32_16x16x32_bf16 v[90:93], v[22:25], v[238:241], v[50:53]
	v_mfma_f32_16x16x32_bf16 v[50:53], v[30:33], v[234:237], v[86:89]
	v_mfma_f32_16x16x32_bf16 v[82:85], v[210:213], v[238:241], v[50:53]
	v_mfma_f32_16x16x32_bf16 v[50:53], v[10:13], v[242:245], v[94:97]
	v_mfma_f32_16x16x32_bf16 v[58:61], v[22:25], v[246:249], v[50:53]
	v_mfma_f32_16x16x32_bf16 v[50:53], v[30:33], v[242:245], v[102:105]
	v_mfma_f32_16x16x32_bf16 v[50:53], v[210:213], v[246:249], v[50:53]
	v_mfma_f32_16x16x32_bf16 v[66:69], v[214:217], v[18:21], v[110:113]
	v_mfma_f32_16x16x32_bf16 v[18:21], v[222:225], v[18:21], v[34:37]
	v_mfma_f32_16x16x32_bf16 v[118:121], v[226:229], v[26:29], v[18:21]
	v_mfma_f32_16x16x32_bf16 v[18:21], v[214:217], v[62:65], v[38:41]
	v_mfma_f32_16x16x32_bf16 v[110:113], v[218:221], v[230:233], v[18:21]
	v_mfma_f32_16x16x32_bf16 v[18:21], v[222:225], v[62:65], v[42:45]
	v_mfma_f32_16x16x32_bf16 v[102:105], v[226:229], v[230:233], v[18:21]
	v_mfma_f32_16x16x32_bf16 v[18:21], v[214:217], v[234:237], v[46:49]
	v_mfma_f32_16x16x32_bf16 v[94:97], v[218:221], v[238:241], v[18:21]
	v_mfma_f32_16x16x32_bf16 v[18:21], v[222:225], v[234:237], v[54:57]
	v_mfma_f32_16x16x32_bf16 v[86:89], v[226:229], v[238:241], v[18:21]
	v_mfma_f32_16x16x32_bf16 v[18:21], v[214:217], v[242:245], v[138:141]
	v_mfma_f32_16x16x32_bf16 v[62:65], v[218:221], v[246:249], v[18:21]
	v_mfma_f32_16x16x32_bf16 v[18:21], v[222:225], v[242:245], v[142:145]
	v_mfma_f32_16x16x32_bf16 v[126:129], v[218:221], v[26:29], v[66:69]
	v_mfma_f32_16x16x32_bf16 v[54:57], v[226:229], v[246:249], v[18:21]
	s_setprio 0
	s_barrier
	s_add_i32 s17, s17, s34
	s_nop 2
	v_lshl_add_u64 v[18:19], v[130:131], 0, s[12:13]
	s_mov_b32 m0, s17
	ds_read_b128 v[38:41], v137 offset:49152
	ds_read_b128 v[46:49], v137 offset:50176
	ds_read_b128 v[138:141], v137 offset:51200
	ds_read_b128 v[142:145], v137 offset:52224
	ds_read_b128 v[230:233], v137 offset:53248
	ds_read_b128 v[234:237], v137 offset:54272
	ds_read_b128 v[238:241], v137 offset:55296
	ds_read_b128 v[242:245], v137 offset:56320
	global_load_lds_dwordx4 v[18:19], off
	s_add_i32 m0, s17, 0x2000
	s_add_u32 s30, s4, 0x40080
	v_lshl_add_u64 v[18:19], v[250:251], 0, s[12:13]
	s_addc_u32 s31, s5, 0
	s_add_i32 s17, s19, s34
	global_load_lds_dwordx4 v[18:19], off
	v_lshl_add_u64 v[18:19], s[30:31], 0, v[182:183]
	s_mov_b32 m0, s17
	s_nop 0
	global_load_lds_dwordx4 v[18:19], off
	v_lshl_add_u64 v[18:19], s[30:31], 0, v[186:187]
	s_add_i32 m0, s17, 0x2000
	s_nop 0
	global_load_lds_dwordx4 v[18:19], off
	v_lshl_add_u64 v[18:19], v[252:253], 0, s[12:13]
	s_mov_b32 m0, s41
	s_nop 0
	global_load_lds_dwordx4 v[18:19], off
	v_lshl_add_u64 v[18:19], v[208:209], 0, s[12:13]
	s_mov_b32 m0, s42
	s_nop 0
	global_load_lds_dwordx4 v[18:19], off
	s_waitcnt vmcnt(8)
	s_waitcnt lgkmcnt(0)
	s_barrier
	s_setprio 1
	v_mfma_f32_16x16x32_bf16 v[18:21], v[10:13], v[38:41], v[146:149]
	v_mfma_f32_16x16x32_bf16 v[74:77], v[22:25], v[46:49], v[18:21]
	v_mfma_f32_16x16x32_bf16 v[18:21], v[30:33], v[38:41], v[150:153]
	v_mfma_f32_16x16x32_bf16 v[66:69], v[210:213], v[46:49], v[18:21]
	v_mfma_f32_16x16x32_bf16 v[18:21], v[10:13], v[138:141], v[154:157]
	v_mfma_f32_16x16x32_bf16 v[42:45], v[22:25], v[142:145], v[18:21]
	v_mfma_f32_16x16x32_bf16 v[18:21], v[30:33], v[138:141], v[158:161]
	v_mfma_f32_16x16x32_bf16 v[34:37], v[210:213], v[142:145], v[18:21]
	v_mfma_f32_16x16x32_bf16 v[18:21], v[10:13], v[230:233], v[162:165]
	v_mfma_f32_16x16x32_bf16 v[2:5], v[10:13], v[238:241], v[2:5]
	v_mfma_f32_16x16x32_bf16 v[26:29], v[22:25], v[234:237], v[18:21]
	v_mfma_f32_16x16x32_bf16 v[18:21], v[30:33], v[230:233], v[166:169]
	v_mfma_f32_16x16x32_bf16 v[10:13], v[22:25], v[242:245], v[2:5]
	v_mfma_f32_16x16x32_bf16 v[2:5], v[30:33], v[238:241], v[6:9]
	v_mfma_f32_16x16x32_bf16 v[18:21], v[210:213], v[234:237], v[18:21]
	v_mfma_f32_16x16x32_bf16 v[2:5], v[210:213], v[242:245], v[2:5]
	v_mfma_f32_16x16x32_bf16 v[6:9], v[214:217], v[38:41], v[14:17]
	v_mfma_f32_16x16x32_bf16 v[78:81], v[218:221], v[46:49], v[6:9]
	v_mfma_f32_16x16x32_bf16 v[6:9], v[222:225], v[38:41], v[170:173]
	v_mfma_f32_16x16x32_bf16 v[70:73], v[226:229], v[46:49], v[6:9]
	v_mfma_f32_16x16x32_bf16 v[6:9], v[214:217], v[138:141], v[174:177]
	v_mfma_f32_16x16x32_bf16 v[46:49], v[218:221], v[142:145], v[6:9]
	v_mfma_f32_16x16x32_bf16 v[6:9], v[222:225], v[138:141], v[188:191]
	v_mfma_f32_16x16x32_bf16 v[38:41], v[226:229], v[142:145], v[6:9]
	v_mfma_f32_16x16x32_bf16 v[6:9], v[214:217], v[230:233], v[192:195]
	v_mfma_f32_16x16x32_bf16 v[30:33], v[218:221], v[234:237], v[6:9]
	v_mfma_f32_16x16x32_bf16 v[6:9], v[222:225], v[230:233], v[196:199]
	v_mfma_f32_16x16x32_bf16 v[22:25], v[226:229], v[234:237], v[6:9]
	v_mfma_f32_16x16x32_bf16 v[6:9], v[214:217], v[238:241], v[200:203]
	v_mfma_f32_16x16x32_bf16 v[14:17], v[218:221], v[242:245], v[6:9]
	v_mfma_f32_16x16x32_bf16 v[6:9], v[222:225], v[238:241], v[204:207]
	v_mfma_f32_16x16x32_bf16 v[6:9], v[226:229], v[242:245], v[6:9]
	s_setprio 0
	s_barrier
	s_andn2_b64 vcc, exec, s[14:15]
	s_cbranch_vccnz .LBB0_1418
	s_barrier

.Lp5_nozero:
.LBB0_1558:
	ds_read_b128 v[146:149], v153
	ds_read_b128 v[156:159], v153 offset:1024
	ds_read_b128 v[160:163], v153 offset:2048
	ds_read_b128 v[164:167], v153 offset:3072
	ds_read_b128 v[168:171], v154
	ds_read_b128 v[172:175], v154 offset:1024
	ds_read_b128 v[180:183], v154 offset:2048
	ds_read_b128 v[184:187], v154 offset:3072
	s_add_u32 s26, s24, 0xfffc0080
	s_addc_u32 s27, s25, -1
	s_cmp_eq_u32 s55, 12
	s_cselect_b32 s29, s17, s27
	s_cselect_b32 s28, s51, s26
	s_cselect_b32 s27, s15, s54
	s_cselect_b32 s26, s52, s53
	v_lshl_add_u64 v[176:177], s[24:25], 0, v[138:139]
	s_add_i32 m0, s23, 0xc000
	ds_read_b128 v[188:191], v155
	ds_read_b128 v[192:195], v155 offset:1024
	ds_read_b128 v[196:199], v155 offset:2048
	ds_read_b128 v[200:203], v155 offset:3072
	ds_read_b128 v[204:207], v155 offset:4096
	ds_read_b128 v[210:213], v155 offset:5120
	ds_read_b128 v[214:217], v155 offset:6144
	ds_read_b128 v[218:221], v155 offset:7168
	global_load_lds_dwordx4 v[176:177], off
	v_lshl_add_u64 v[176:177], s[24:25], 0, v[140:141]
	s_add_i32 m0, s23, 0xe000
	s_nop 0
	global_load_lds_dwordx4 v[176:177], off
	s_waitcnt vmcnt(8)
	s_waitcnt lgkmcnt(0)
	s_barrier
	s_setprio 1
	v_mfma_f32_16x16x32_bf16 v[122:125], v[146:149], v[188:191], v[122:125]
	v_mfma_f32_16x16x32_bf16 v[114:117], v[160:163], v[188:191], v[114:117]
	v_mfma_f32_16x16x32_bf16 v[106:109], v[146:149], v[196:199], v[106:109]
	v_mfma_f32_16x16x32_bf16 v[98:101], v[160:163], v[196:199], v[98:101]
	v_mfma_f32_16x16x32_bf16 v[90:93], v[146:149], v[204:207], v[90:93]
	v_mfma_f32_16x16x32_bf16 v[82:85], v[160:163], v[204:207], v[82:85]
	v_mfma_f32_16x16x32_bf16 v[74:77], v[146:149], v[214:217], v[74:77]
	v_mfma_f32_16x16x32_bf16 v[70:73], v[160:163], v[214:217], v[70:73]
	v_mfma_f32_16x16x32_bf16 v[122:125], v[156:159], v[192:195], v[122:125]
	v_mfma_f32_16x16x32_bf16 v[114:117], v[164:167], v[192:195], v[114:117]
	v_mfma_f32_16x16x32_bf16 v[106:109], v[156:159], v[200:203], v[106:109]
	v_mfma_f32_16x16x32_bf16 v[98:101], v[164:167], v[200:203], v[98:101]
	v_mfma_f32_16x16x32_bf16 v[90:93], v[156:159], v[210:213], v[90:93]
	v_mfma_f32_16x16x32_bf16 v[82:85], v[164:167], v[210:213], v[82:85]
	v_mfma_f32_16x16x32_bf16 v[74:77], v[156:159], v[218:221], v[74:77]
	v_mfma_f32_16x16x32_bf16 v[70:73], v[164:167], v[218:221], v[70:73]
	v_mfma_f32_16x16x32_bf16 v[126:129], v[168:171], v[188:191], v[126:129]
	v_mfma_f32_16x16x32_bf16 v[118:121], v[180:183], v[188:191], v[118:121]
	v_mfma_f32_16x16x32_bf16 v[110:113], v[168:171], v[196:199], v[110:113]
	v_mfma_f32_16x16x32_bf16 v[102:105], v[180:183], v[196:199], v[102:105]
	v_mfma_f32_16x16x32_bf16 v[94:97], v[168:171], v[204:207], v[94:97]
	v_mfma_f32_16x16x32_bf16 v[86:89], v[180:183], v[204:207], v[86:89]
	v_mfma_f32_16x16x32_bf16 v[78:81], v[168:171], v[214:217], v[78:81]
	v_mfma_f32_16x16x32_bf16 v[66:69], v[180:183], v[214:217], v[66:69]
	v_mfma_f32_16x16x32_bf16 v[126:129], v[172:175], v[192:195], v[126:129]
	v_mfma_f32_16x16x32_bf16 v[118:121], v[184:187], v[192:195], v[118:121]
	v_mfma_f32_16x16x32_bf16 v[110:113], v[172:175], v[200:203], v[110:113]
	v_mfma_f32_16x16x32_bf16 v[102:105], v[184:187], v[200:203], v[102:105]
	v_mfma_f32_16x16x32_bf16 v[94:97], v[172:175], v[210:213], v[94:97]
	v_mfma_f32_16x16x32_bf16 v[86:89], v[184:187], v[210:213], v[86:89]
	v_mfma_f32_16x16x32_bf16 v[78:81], v[172:175], v[218:221], v[78:81]
	v_mfma_f32_16x16x32_bf16 v[66:69], v[184:187], v[218:221], v[66:69]
	s_setprio 0
	s_barrier
	s_add_i32 s56, s45, s35
	v_lshl_add_u64 v[176:177], s[26:27], 0, v[134:135]
	s_mov_b32 m0, s56
	ds_read_b128 v[188:191], v155 offset:16384
	ds_read_b128 v[192:195], v155 offset:17408
	ds_read_b128 v[196:199], v155 offset:18432
	ds_read_b128 v[200:203], v155 offset:19456
	ds_read_b128 v[204:207], v155 offset:20480
	ds_read_b128 v[210:213], v155 offset:21504
	ds_read_b128 v[214:217], v155 offset:22528
	ds_read_b128 v[218:221], v155 offset:23552
	global_load_lds_dwordx4 v[176:177], off
	s_add_i32 m0, s56, 0x2000
	s_add_u32 s56, s26, 0x40000
	v_lshl_add_u64 v[208:209], s[26:27], 0, v[130:131]
	s_addc_u32 s57, s27, 0
	s_add_i32 s58, s48, s35
	global_load_lds_dwordx4 v[208:209], off
	v_lshl_add_u64 v[222:223], s[56:57], 0, v[134:135]
	s_mov_b32 m0, s58
	v_lshl_add_u64 v[224:225], s[28:29], 0, v[132:133]
	global_load_lds_dwordx4 v[222:223], off
	v_lshl_add_u64 v[222:223], s[56:57], 0, v[130:131]
	s_add_i32 m0, s58, 0x2000
	s_nop 0
	global_load_lds_dwordx4 v[222:223], off
	v_lshl_add_u64 v[222:223], s[28:29], 0, v[136:137]
	s_mov_b32 m0, s23
	s_nop 0
	global_load_lds_dwordx4 v[222:223], off
	s_mov_b32 m0, s38
	s_nop 0
	global_load_lds_dwordx4 v[224:225], off
	s_waitcnt vmcnt(8)
	s_waitcnt lgkmcnt(0)
	s_barrier
	s_setprio 1
	v_mfma_f32_16x16x32_bf16 v[58:61], v[146:149], v[188:191], v[58:61]
	v_mfma_f32_16x16x32_bf16 v[54:57], v[160:163], v[188:191], v[54:57]
	v_mfma_f32_16x16x32_bf16 v[42:45], v[146:149], v[196:199], v[42:45]
	v_mfma_f32_16x16x32_bf16 v[38:41], v[160:163], v[196:199], v[38:41]
	v_mfma_f32_16x16x32_bf16 v[26:29], v[146:149], v[204:207], v[26:29]
	v_mfma_f32_16x16x32_bf16 v[22:25], v[160:163], v[204:207], v[22:25]
	v_mfma_f32_16x16x32_bf16 v[10:13], v[146:149], v[214:217], v[10:13]
	v_mfma_f32_16x16x32_bf16 v[6:9], v[160:163], v[214:217], v[6:9]
	v_mfma_f32_16x16x32_bf16 v[58:61], v[156:159], v[192:195], v[58:61]
	v_mfma_f32_16x16x32_bf16 v[54:57], v[164:167], v[192:195], v[54:57]
	v_mfma_f32_16x16x32_bf16 v[42:45], v[156:159], v[200:203], v[42:45]
	v_mfma_f32_16x16x32_bf16 v[38:41], v[164:167], v[200:203], v[38:41]
	v_mfma_f32_16x16x32_bf16 v[26:29], v[156:159], v[210:213], v[26:29]
	v_mfma_f32_16x16x32_bf16 v[22:25], v[164:167], v[210:213], v[22:25]
	v_mfma_f32_16x16x32_bf16 v[10:13], v[156:159], v[218:221], v[10:13]
	v_mfma_f32_16x16x32_bf16 v[6:9], v[164:167], v[218:221], v[6:9]
	v_mfma_f32_16x16x32_bf16 v[62:65], v[168:171], v[188:191], v[62:65]
	v_mfma_f32_16x16x32_bf16 v[50:53], v[180:183], v[188:191], v[50:53]
	v_mfma_f32_16x16x32_bf16 v[46:49], v[168:171], v[196:199], v[46:49]
	v_mfma_f32_16x16x32_bf16 v[34:37], v[180:183], v[196:199], v[34:37]
	v_mfma_f32_16x16x32_bf16 v[30:33], v[168:171], v[204:207], v[30:33]
	v_mfma_f32_16x16x32_bf16 v[18:21], v[180:183], v[204:207], v[18:21]
	v_mfma_f32_16x16x32_bf16 v[14:17], v[168:171], v[214:217], v[14:17]
	v_mfma_f32_16x16x32_bf16 v[2:5], v[180:183], v[214:217], v[2:5]
	v_mfma_f32_16x16x32_bf16 v[62:65], v[172:175], v[192:195], v[62:65]
	v_mfma_f32_16x16x32_bf16 v[50:53], v[184:187], v[192:195], v[50:53]
	v_mfma_f32_16x16x32_bf16 v[46:49], v[172:175], v[200:203], v[46:49]
	v_mfma_f32_16x16x32_bf16 v[34:37], v[184:187], v[200:203], v[34:37]
	v_mfma_f32_16x16x32_bf16 v[30:33], v[172:175], v[210:213], v[30:33]
	v_mfma_f32_16x16x32_bf16 v[18:21], v[184:187], v[210:213], v[18:21]
	v_mfma_f32_16x16x32_bf16 v[14:17], v[172:175], v[218:221], v[14:17]
	v_mfma_f32_16x16x32_bf16 v[2:5], v[184:187], v[218:221], v[2:5]
	s_setprio 0
	s_barrier
	s_add_i32 s56, 0, 0x18000
	s_add_i32 s57, 0, 0x1c000
	v_add_u32_e32 v164, s56, v151
	v_add_u32_e32 v179, s57, v151
	ds_read_b128 v[146:149], v164
	ds_read_b128 v[156:159], v164 offset:1024
	ds_read_b128 v[160:163], v164 offset:2048
	ds_read_b128 v[164:167], v164 offset:3072
	ds_read_b128 v[168:171], v179
	ds_read_b128 v[172:175], v179 offset:1024
	ds_read_b128 v[180:183], v179 offset:2048
	ds_read_b128 v[184:187], v179 offset:3072
	s_add_u32 s28, s28, 0x40000
	s_addc_u32 s29, s29, 0
	s_mov_b32 m0, s39
	v_lshl_add_u64 v[226:227], s[28:29], 0, v[136:137]
	ds_read_b128 v[188:191], v155 offset:32768
	ds_read_b128 v[192:195], v155 offset:33792
	ds_read_b128 v[196:199], v155 offset:34816
	ds_read_b128 v[200:203], v155 offset:35840
	ds_read_b128 v[204:207], v155 offset:36864
	ds_read_b128 v[210:213], v155 offset:37888
	ds_read_b128 v[214:217], v155 offset:38912
	ds_read_b128 v[218:221], v155 offset:39936
	global_load_lds_dwordx4 v[226:227], off
	v_lshl_add_u64 v[226:227], s[28:29], 0, v[132:133]
	s_mov_b32 m0, s40
	s_nop 0
	global_load_lds_dwordx4 v[226:227], off
	s_waitcnt vmcnt(8)
	s_waitcnt lgkmcnt(0)
	s_barrier
	s_setprio 1
	v_mfma_f32_16x16x32_bf16 v[122:125], v[146:149], v[188:191], v[122:125]
	v_mfma_f32_16x16x32_bf16 v[114:117], v[160:163], v[188:191], v[114:117]
	v_mfma_f32_16x16x32_bf16 v[106:109], v[146:149], v[196:199], v[106:109]
	v_mfma_f32_16x16x32_bf16 v[98:101], v[160:163], v[196:199], v[98:101]
	v_mfma_f32_16x16x32_bf16 v[90:93], v[146:149], v[204:207], v[90:93]
	v_mfma_f32_16x16x32_bf16 v[82:85], v[160:163], v[204:207], v[82:85]
	v_mfma_f32_16x16x32_bf16 v[74:77], v[146:149], v[214:217], v[74:77]
	v_mfma_f32_16x16x32_bf16 v[70:73], v[160:163], v[214:217], v[70:73]
	v_mfma_f32_16x16x32_bf16 v[122:125], v[156:159], v[192:195], v[122:125]
	v_mfma_f32_16x16x32_bf16 v[114:117], v[164:167], v[192:195], v[114:117]
	v_mfma_f32_16x16x32_bf16 v[106:109], v[156:159], v[200:203], v[106:109]
	v_mfma_f32_16x16x32_bf16 v[98:101], v[164:167], v[200:203], v[98:101]
	v_mfma_f32_16x16x32_bf16 v[90:93], v[156:159], v[210:213], v[90:93]
	v_mfma_f32_16x16x32_bf16 v[82:85], v[164:167], v[210:213], v[82:85]
	v_mfma_f32_16x16x32_bf16 v[74:77], v[156:159], v[218:221], v[74:77]
	v_mfma_f32_16x16x32_bf16 v[70:73], v[164:167], v[218:221], v[70:73]
	v_mfma_f32_16x16x32_bf16 v[126:129], v[168:171], v[188:191], v[126:129]
	v_mfma_f32_16x16x32_bf16 v[118:121], v[180:183], v[188:191], v[118:121]
	v_mfma_f32_16x16x32_bf16 v[110:113], v[168:171], v[196:199], v[110:113]
	v_mfma_f32_16x16x32_bf16 v[102:105], v[180:183], v[196:199], v[102:105]
	v_mfma_f32_16x16x32_bf16 v[94:97], v[168:171], v[204:207], v[94:97]
	v_mfma_f32_16x16x32_bf16 v[86:89], v[180:183], v[204:207], v[86:89]
	v_mfma_f32_16x16x32_bf16 v[78:81], v[168:171], v[214:217], v[78:81]
	v_mfma_f32_16x16x32_bf16 v[66:69], v[180:183], v[214:217], v[66:69]
	v_mfma_f32_16x16x32_bf16 v[126:129], v[172:175], v[192:195], v[126:129]
	v_mfma_f32_16x16x32_bf16 v[118:121], v[184:187], v[192:195], v[118:121]
	v_mfma_f32_16x16x32_bf16 v[110:113], v[172:175], v[200:203], v[110:113]
	v_mfma_f32_16x16x32_bf16 v[102:105], v[184:187], v[200:203], v[102:105]
	v_mfma_f32_16x16x32_bf16 v[94:97], v[172:175], v[210:213], v[94:97]
	v_mfma_f32_16x16x32_bf16 v[86:89], v[184:187], v[210:213], v[86:89]
	v_mfma_f32_16x16x32_bf16 v[78:81], v[172:175], v[218:221], v[78:81]
	v_mfma_f32_16x16x32_bf16 v[66:69], v[184:187], v[218:221], v[66:69]
	s_setprio 0
	s_barrier
	s_add_i32 s28, s56, s35
	v_lshl_add_u64 v[176:177], v[176:177], 0, s[10:11]
	s_mov_b32 m0, s28
	ds_read_b128 v[188:191], v155 offset:49152
	ds_read_b128 v[192:195], v155 offset:50176
	ds_read_b128 v[196:199], v155 offset:51200
	ds_read_b128 v[200:203], v155 offset:52224
	ds_read_b128 v[204:207], v155 offset:53248
	ds_read_b128 v[210:213], v155 offset:54272
	ds_read_b128 v[214:217], v155 offset:55296
	ds_read_b128 v[218:221], v155 offset:56320
	global_load_lds_dwordx4 v[176:177], off
	s_add_i32 m0, s28, 0x2000
	s_add_u32 s26, s26, 0x40080
	v_lshl_add_u64 v[176:177], v[208:209], 0, s[10:11]
	s_addc_u32 s27, s27, 0
	s_add_i32 s28, s57, s35
	global_load_lds_dwordx4 v[176:177], off
	v_lshl_add_u64 v[176:177], s[26:27], 0, v[134:135]
	s_mov_b32 m0, s28
	s_nop 0
	global_load_lds_dwordx4 v[176:177], off
	v_lshl_add_u64 v[176:177], s[26:27], 0, v[130:131]
	s_add_i32 m0, s28, 0x2000
	s_nop 0
	global_load_lds_dwordx4 v[176:177], off
	v_lshl_add_u64 v[176:177], v[222:223], 0, s[10:11]
	s_mov_b32 m0, s42
	s_nop 0
	global_load_lds_dwordx4 v[176:177], off
	v_lshl_add_u64 v[176:177], v[224:225], 0, s[10:11]
	s_mov_b32 m0, s43
	s_nop 0
	global_load_lds_dwordx4 v[176:177], off
	s_waitcnt vmcnt(8)
	s_waitcnt lgkmcnt(0)
	s_barrier
	s_setprio 1
	v_mfma_f32_16x16x32_bf16 v[58:61], v[146:149], v[188:191], v[58:61]
	v_mfma_f32_16x16x32_bf16 v[54:57], v[160:163], v[188:191], v[54:57]
	v_mfma_f32_16x16x32_bf16 v[42:45], v[146:149], v[196:199], v[42:45]
	v_mfma_f32_16x16x32_bf16 v[38:41], v[160:163], v[196:199], v[38:41]
	v_mfma_f32_16x16x32_bf16 v[26:29], v[146:149], v[204:207], v[26:29]
	v_mfma_f32_16x16x32_bf16 v[22:25], v[160:163], v[204:207], v[22:25]
	v_mfma_f32_16x16x32_bf16 v[10:13], v[146:149], v[214:217], v[10:13]
	v_mfma_f32_16x16x32_bf16 v[6:9], v[160:163], v[214:217], v[6:9]
	v_mfma_f32_16x16x32_bf16 v[58:61], v[156:159], v[192:195], v[58:61]
	v_mfma_f32_16x16x32_bf16 v[54:57], v[164:167], v[192:195], v[54:57]
	v_mfma_f32_16x16x32_bf16 v[42:45], v[156:159], v[200:203], v[42:45]
	v_mfma_f32_16x16x32_bf16 v[38:41], v[164:167], v[200:203], v[38:41]
	v_mfma_f32_16x16x32_bf16 v[26:29], v[156:159], v[210:213], v[26:29]
	v_mfma_f32_16x16x32_bf16 v[22:25], v[164:167], v[210:213], v[22:25]
	v_mfma_f32_16x16x32_bf16 v[10:13], v[156:159], v[218:221], v[10:13]
	v_mfma_f32_16x16x32_bf16 v[6:9], v[164:167], v[218:221], v[6:9]
	v_mfma_f32_16x16x32_bf16 v[62:65], v[168:171], v[188:191], v[62:65]
	v_mfma_f32_16x16x32_bf16 v[50:53], v[180:183], v[188:191], v[50:53]
	v_mfma_f32_16x16x32_bf16 v[46:49], v[168:171], v[196:199], v[46:49]
	v_mfma_f32_16x16x32_bf16 v[34:37], v[180:183], v[196:199], v[34:37]
	v_mfma_f32_16x16x32_bf16 v[30:33], v[168:171], v[204:207], v[30:33]
	v_mfma_f32_16x16x32_bf16 v[18:21], v[180:183], v[204:207], v[18:21]
	v_mfma_f32_16x16x32_bf16 v[14:17], v[168:171], v[214:217], v[14:17]
	v_mfma_f32_16x16x32_bf16 v[2:5], v[180:183], v[214:217], v[2:5]
	v_mfma_f32_16x16x32_bf16 v[62:65], v[172:175], v[192:195], v[62:65]
	v_mfma_f32_16x16x32_bf16 v[50:53], v[184:187], v[192:195], v[50:53]
	v_mfma_f32_16x16x32_bf16 v[46:49], v[172:175], v[200:203], v[46:49]
	v_mfma_f32_16x16x32_bf16 v[34:37], v[184:187], v[200:203], v[34:37]
	v_mfma_f32_16x16x32_bf16 v[30:33], v[172:175], v[210:213], v[30:33]
	v_mfma_f32_16x16x32_bf16 v[18:21], v[184:187], v[210:213], v[18:21]
	v_mfma_f32_16x16x32_bf16 v[14:17], v[172:175], v[218:221], v[14:17]
	v_mfma_f32_16x16x32_bf16 v[2:5], v[184:187], v[218:221], v[2:5]
	s_setprio 0
	s_barrier
	s_add_i32 s55, s55, 2
	s_add_u32 s24, s24, 0x100
	s_addc_u32 s25, s25, 0
	s_add_u32 s53, s53, 0x100
	s_addc_u32 s54, s54, 0
	s_cmp_gt_u32 s55, 13
	s_cbranch_scc0 .LBB0_1558
	s_and_b64 vcc, exec, s[12:13]
	s_cbranch_vccz .LBB0_1561
	s_barrier

.LBB0_1652:
	ds_read_b128 v[150:153], v161
	ds_read_b128 v[164:167], v161 offset:1024
	ds_read_b128 v[168:171], v161 offset:2048
	ds_read_b128 v[172:175], v161 offset:3072
	ds_read_b128 v[180:183], v162
	ds_read_b128 v[184:187], v162 offset:1024
	ds_read_b128 v[196:199], v162 offset:2048
	ds_read_b128 v[200:203], v162 offset:3072
	s_add_u32 s18, s16, 0xfff50080
	s_addc_u32 s19, s17, -1
	s_cmp_eq_u32 s41, 40
	s_cselect_b32 s21, s5, s19
	s_cselect_b32 s20, s4, s18
	s_cselect_b32 s19, s15, s40
	s_cselect_b32 s18, s14, s39
	v_lshl_add_u64 v[154:155], s[16:17], 0, v[142:143]
	s_add_i32 m0, s24, 0xc000
	ds_read_b128 v[204:207], v163
	ds_read_b128 v[210:213], v163 offset:1024
	ds_read_b128 v[214:217], v163 offset:2048
	ds_read_b128 v[218:221], v163 offset:3072
	ds_read_b128 v[222:225], v163 offset:4096
	ds_read_b128 v[226:229], v163 offset:5120
	ds_read_b128 v[230:233], v163 offset:6144
	ds_read_b128 v[234:237], v163 offset:7168
	global_load_lds_dwordx4 v[154:155], off
	v_lshl_add_u64 v[154:155], s[16:17], 0, v[144:145]
	s_add_i32 m0, s24, 0xe000
	s_nop 0
	global_load_lds_dwordx4 v[154:155], off
	s_waitcnt vmcnt(8)
	s_waitcnt lgkmcnt(0)
	s_barrier
	s_setprio 1
	v_mfma_f32_16x16x32_bf16 v[126:129], v[150:153], v[204:207], v[126:129]
	v_mfma_f32_16x16x32_bf16 v[122:125], v[168:171], v[204:207], v[122:125]
	v_mfma_f32_16x16x32_bf16 v[110:113], v[150:153], v[214:217], v[110:113]
	v_mfma_f32_16x16x32_bf16 v[106:109], v[168:171], v[214:217], v[106:109]
	v_mfma_f32_16x16x32_bf16 v[94:97], v[150:153], v[222:225], v[94:97]
	v_mfma_f32_16x16x32_bf16 v[90:93], v[168:171], v[222:225], v[90:93]
	v_mfma_f32_16x16x32_bf16 v[78:81], v[150:153], v[230:233], v[78:81]
	v_mfma_f32_16x16x32_bf16 v[74:77], v[168:171], v[230:233], v[74:77]
	v_mfma_f32_16x16x32_bf16 v[126:129], v[164:167], v[210:213], v[126:129]
	v_mfma_f32_16x16x32_bf16 v[122:125], v[172:175], v[210:213], v[122:125]
	v_mfma_f32_16x16x32_bf16 v[110:113], v[164:167], v[218:221], v[110:113]
	v_mfma_f32_16x16x32_bf16 v[106:109], v[172:175], v[218:221], v[106:109]
	v_mfma_f32_16x16x32_bf16 v[94:97], v[164:167], v[226:229], v[94:97]
	v_mfma_f32_16x16x32_bf16 v[90:93], v[172:175], v[226:229], v[90:93]
	v_mfma_f32_16x16x32_bf16 v[78:81], v[164:167], v[234:237], v[78:81]
	v_mfma_f32_16x16x32_bf16 v[74:77], v[172:175], v[234:237], v[74:77]
	v_mfma_f32_16x16x32_bf16 v[118:121], v[180:183], v[204:207], v[118:121]
	v_mfma_f32_16x16x32_bf16 v[114:117], v[196:199], v[204:207], v[114:117]
	v_mfma_f32_16x16x32_bf16 v[102:105], v[180:183], v[214:217], v[102:105]
	v_mfma_f32_16x16x32_bf16 v[98:101], v[196:199], v[214:217], v[98:101]
	v_mfma_f32_16x16x32_bf16 v[86:89], v[180:183], v[222:225], v[86:89]
	v_mfma_f32_16x16x32_bf16 v[82:85], v[196:199], v[222:225], v[82:85]
	v_mfma_f32_16x16x32_bf16 v[70:73], v[180:183], v[230:233], v[70:73]
	v_mfma_f32_16x16x32_bf16 v[66:69], v[196:199], v[230:233], v[66:69]
	v_mfma_f32_16x16x32_bf16 v[118:121], v[184:187], v[210:213], v[118:121]
	v_mfma_f32_16x16x32_bf16 v[114:117], v[200:203], v[210:213], v[114:117]
	v_mfma_f32_16x16x32_bf16 v[102:105], v[184:187], v[218:221], v[102:105]
	v_mfma_f32_16x16x32_bf16 v[98:101], v[200:203], v[218:221], v[98:101]
	v_mfma_f32_16x16x32_bf16 v[86:89], v[184:187], v[226:229], v[86:89]
	v_mfma_f32_16x16x32_bf16 v[82:85], v[200:203], v[226:229], v[82:85]
	v_mfma_f32_16x16x32_bf16 v[70:73], v[184:187], v[234:237], v[70:73]
	v_mfma_f32_16x16x32_bf16 v[66:69], v[200:203], v[234:237], v[66:69]
	s_setprio 0
	s_barrier
	s_add_i32 s42, s33, s23
	v_lshl_add_u64 v[154:155], s[18:19], 0, v[132:133]
	s_mov_b32 m0, s42
	ds_read_b128 v[204:207], v163 offset:16384
	ds_read_b128 v[210:213], v163 offset:17408
	ds_read_b128 v[214:217], v163 offset:18432
	ds_read_b128 v[218:221], v163 offset:19456
	ds_read_b128 v[222:225], v163 offset:20480
	ds_read_b128 v[226:229], v163 offset:21504
	ds_read_b128 v[230:233], v163 offset:22528
	ds_read_b128 v[234:237], v163 offset:23552
	global_load_lds_dwordx4 v[154:155], off
	s_add_i32 m0, s42, 0x2000
	s_add_u32 s42, s18, 0xb0000
	v_lshl_add_u64 v[176:177], s[18:19], 0, v[136:137]
	s_addc_u32 s43, s19, 0
	s_add_i32 s44, s34, s23
	global_load_lds_dwordx4 v[176:177], off
	v_lshl_add_u64 v[188:189], s[42:43], 0, v[132:133]
	s_mov_b32 m0, s44
	v_lshl_add_u64 v[208:209], s[20:21], 0, v[134:135]
	global_load_lds_dwordx4 v[188:189], off
	v_lshl_add_u64 v[188:189], s[42:43], 0, v[136:137]
	s_add_i32 m0, s44, 0x2000
	s_nop 0
	global_load_lds_dwordx4 v[188:189], off
	v_lshl_add_u64 v[188:189], s[20:21], 0, v[130:131]
	s_mov_b32 m0, s24
	s_nop 0
	global_load_lds_dwordx4 v[188:189], off
	s_mov_b32 m0, s25
	s_nop 0
	global_load_lds_dwordx4 v[208:209], off
	s_waitcnt vmcnt(8)
	s_waitcnt lgkmcnt(0)
	s_barrier
	s_setprio 1
	v_mfma_f32_16x16x32_bf16 v[62:65], v[150:153], v[204:207], v[62:65]
	v_mfma_f32_16x16x32_bf16 v[58:61], v[168:171], v[204:207], v[58:61]
	v_mfma_f32_16x16x32_bf16 v[46:49], v[150:153], v[214:217], v[46:49]
	v_mfma_f32_16x16x32_bf16 v[42:45], v[168:171], v[214:217], v[42:45]
	v_mfma_f32_16x16x32_bf16 v[30:33], v[150:153], v[222:225], v[30:33]
	v_mfma_f32_16x16x32_bf16 v[26:29], v[168:171], v[222:225], v[26:29]
	v_mfma_f32_16x16x32_bf16 v[14:17], v[150:153], v[230:233], v[14:17]
	v_mfma_f32_16x16x32_bf16 v[10:13], v[168:171], v[230:233], v[10:13]
	v_mfma_f32_16x16x32_bf16 v[62:65], v[164:167], v[210:213], v[62:65]
	v_mfma_f32_16x16x32_bf16 v[58:61], v[172:175], v[210:213], v[58:61]
	v_mfma_f32_16x16x32_bf16 v[46:49], v[164:167], v[218:221], v[46:49]
	v_mfma_f32_16x16x32_bf16 v[42:45], v[172:175], v[218:221], v[42:45]
	v_mfma_f32_16x16x32_bf16 v[30:33], v[164:167], v[226:229], v[30:33]
	v_mfma_f32_16x16x32_bf16 v[26:29], v[172:175], v[226:229], v[26:29]
	v_mfma_f32_16x16x32_bf16 v[14:17], v[164:167], v[234:237], v[14:17]
	v_mfma_f32_16x16x32_bf16 v[10:13], v[172:175], v[234:237], v[10:13]
	v_mfma_f32_16x16x32_bf16 v[54:57], v[180:183], v[204:207], v[54:57]
	v_mfma_f32_16x16x32_bf16 v[50:53], v[196:199], v[204:207], v[50:53]
	v_mfma_f32_16x16x32_bf16 v[38:41], v[180:183], v[214:217], v[38:41]
	v_mfma_f32_16x16x32_bf16 v[34:37], v[196:199], v[214:217], v[34:37]
	v_mfma_f32_16x16x32_bf16 v[22:25], v[180:183], v[222:225], v[22:25]
	v_mfma_f32_16x16x32_bf16 v[18:21], v[196:199], v[222:225], v[18:21]
	v_mfma_f32_16x16x32_bf16 v[6:9], v[180:183], v[230:233], v[6:9]
	v_mfma_f32_16x16x32_bf16 v[2:5], v[196:199], v[230:233], v[2:5]
	v_mfma_f32_16x16x32_bf16 v[54:57], v[184:187], v[210:213], v[54:57]
	v_mfma_f32_16x16x32_bf16 v[50:53], v[200:203], v[210:213], v[50:53]
	v_mfma_f32_16x16x32_bf16 v[38:41], v[184:187], v[218:221], v[38:41]
	v_mfma_f32_16x16x32_bf16 v[34:37], v[200:203], v[218:221], v[34:37]
	v_mfma_f32_16x16x32_bf16 v[22:25], v[184:187], v[226:229], v[22:25]
	v_mfma_f32_16x16x32_bf16 v[18:21], v[200:203], v[226:229], v[18:21]
	v_mfma_f32_16x16x32_bf16 v[6:9], v[184:187], v[234:237], v[6:9]
	v_mfma_f32_16x16x32_bf16 v[2:5], v[200:203], v[234:237], v[2:5]
	s_setprio 0
	s_barrier
	s_add_i32 s42, 0, 0x18000
	v_add_u32_e32 v139, s42, v159
	s_add_i32 s43, 0, 0x1c000
	ds_read_b128 v[150:153], v139
	ds_read_b128 v[164:167], v139 offset:1024
	ds_read_b128 v[168:171], v139 offset:2048
	ds_read_b128 v[172:175], v139 offset:3072
	v_add_u32_e32 v139, s43, v159
	ds_read_b128 v[180:183], v139
	ds_read_b128 v[184:187], v139 offset:1024
	ds_read_b128 v[196:199], v139 offset:2048
	ds_read_b128 v[200:203], v139 offset:3072
	s_add_u32 s20, s20, 0xb0000
	s_addc_u32 s21, s21, 0
	s_mov_b32 m0, s26
	v_lshl_add_u64 v[238:239], s[20:21], 0, v[130:131]
	ds_read_b128 v[204:207], v163 offset:32768
	ds_read_b128 v[210:213], v163 offset:33792
	ds_read_b128 v[214:217], v163 offset:34816
	ds_read_b128 v[218:221], v163 offset:35840
	ds_read_b128 v[222:225], v163 offset:36864
	ds_read_b128 v[226:229], v163 offset:37888
	ds_read_b128 v[230:233], v163 offset:38912
	ds_read_b128 v[234:237], v163 offset:39936
	global_load_lds_dwordx4 v[238:239], off
	v_lshl_add_u64 v[238:239], s[20:21], 0, v[134:135]
	s_mov_b32 m0, s27
	s_nop 0
	global_load_lds_dwordx4 v[238:239], off
	s_waitcnt vmcnt(8)
	s_waitcnt lgkmcnt(0)
	s_barrier
	s_setprio 1
	v_mfma_f32_16x16x32_bf16 v[126:129], v[150:153], v[204:207], v[126:129]
	v_mfma_f32_16x16x32_bf16 v[122:125], v[168:171], v[204:207], v[122:125]
	v_mfma_f32_16x16x32_bf16 v[110:113], v[150:153], v[214:217], v[110:113]
	v_mfma_f32_16x16x32_bf16 v[106:109], v[168:171], v[214:217], v[106:109]
	v_mfma_f32_16x16x32_bf16 v[94:97], v[150:153], v[222:225], v[94:97]
	v_mfma_f32_16x16x32_bf16 v[90:93], v[168:171], v[222:225], v[90:93]
	v_mfma_f32_16x16x32_bf16 v[78:81], v[150:153], v[230:233], v[78:81]
	v_mfma_f32_16x16x32_bf16 v[74:77], v[168:171], v[230:233], v[74:77]
	v_mfma_f32_16x16x32_bf16 v[126:129], v[164:167], v[210:213], v[126:129]
	v_mfma_f32_16x16x32_bf16 v[122:125], v[172:175], v[210:213], v[122:125]
	v_mfma_f32_16x16x32_bf16 v[110:113], v[164:167], v[218:221], v[110:113]
	v_mfma_f32_16x16x32_bf16 v[106:109], v[172:175], v[218:221], v[106:109]
	v_mfma_f32_16x16x32_bf16 v[94:97], v[164:167], v[226:229], v[94:97]
	v_mfma_f32_16x16x32_bf16 v[90:93], v[172:175], v[226:229], v[90:93]
	v_mfma_f32_16x16x32_bf16 v[78:81], v[164:167], v[234:237], v[78:81]
	v_mfma_f32_16x16x32_bf16 v[74:77], v[172:175], v[234:237], v[74:77]
	v_mfma_f32_16x16x32_bf16 v[118:121], v[180:183], v[204:207], v[118:121]
	v_mfma_f32_16x16x32_bf16 v[114:117], v[196:199], v[204:207], v[114:117]
	v_mfma_f32_16x16x32_bf16 v[102:105], v[180:183], v[214:217], v[102:105]
	v_mfma_f32_16x16x32_bf16 v[98:101], v[196:199], v[214:217], v[98:101]
	v_mfma_f32_16x16x32_bf16 v[86:89], v[180:183], v[222:225], v[86:89]
	v_mfma_f32_16x16x32_bf16 v[82:85], v[196:199], v[222:225], v[82:85]
	v_mfma_f32_16x16x32_bf16 v[70:73], v[180:183], v[230:233], v[70:73]
	v_mfma_f32_16x16x32_bf16 v[66:69], v[196:199], v[230:233], v[66:69]
	v_mfma_f32_16x16x32_bf16 v[118:121], v[184:187], v[210:213], v[118:121]
	v_mfma_f32_16x16x32_bf16 v[114:117], v[200:203], v[210:213], v[114:117]
	v_mfma_f32_16x16x32_bf16 v[102:105], v[184:187], v[218:221], v[102:105]
	v_mfma_f32_16x16x32_bf16 v[98:101], v[200:203], v[218:221], v[98:101]
	v_mfma_f32_16x16x32_bf16 v[86:89], v[184:187], v[226:229], v[86:89]
	v_mfma_f32_16x16x32_bf16 v[82:85], v[200:203], v[226:229], v[82:85]
	v_mfma_f32_16x16x32_bf16 v[70:73], v[184:187], v[234:237], v[70:73]
	v_mfma_f32_16x16x32_bf16 v[66:69], v[200:203], v[234:237], v[66:69]
	s_setprio 0
	s_barrier
	s_add_i32 s20, s42, s23
	v_lshl_add_u64 v[154:155], v[154:155], 0, s[10:11]
	s_mov_b32 m0, s20
	ds_read_b128 v[204:207], v163 offset:49152
	ds_read_b128 v[210:213], v163 offset:50176
	ds_read_b128 v[214:217], v163 offset:51200
	ds_read_b128 v[218:221], v163 offset:52224
	ds_read_b128 v[222:225], v163 offset:53248
	ds_read_b128 v[226:229], v163 offset:54272
	ds_read_b128 v[230:233], v163 offset:55296
	ds_read_b128 v[234:237], v163 offset:56320
	global_load_lds_dwordx4 v[154:155], off
	s_add_i32 m0, s20, 0x2000
	s_add_u32 s18, s18, 0xb0080
	v_lshl_add_u64 v[154:155], v[176:177], 0, s[10:11]
	s_addc_u32 s19, s19, 0
	s_add_i32 s20, s43, s23
	global_load_lds_dwordx4 v[154:155], off
	v_lshl_add_u64 v[154:155], s[18:19], 0, v[132:133]
	s_mov_b32 m0, s20
	s_nop 0
	global_load_lds_dwordx4 v[154:155], off
	v_lshl_add_u64 v[154:155], s[18:19], 0, v[136:137]
	s_add_i32 m0, s20, 0x2000
	s_nop 0
	global_load_lds_dwordx4 v[154:155], off
	v_lshl_add_u64 v[154:155], v[188:189], 0, s[10:11]
	s_mov_b32 m0, s29
	s_nop 0
	global_load_lds_dwordx4 v[154:155], off
	v_lshl_add_u64 v[154:155], v[208:209], 0, s[10:11]
	s_mov_b32 m0, s30
	s_nop 0
	global_load_lds_dwordx4 v[154:155], off
	s_waitcnt vmcnt(8)
	s_waitcnt lgkmcnt(0)
	s_barrier
	s_setprio 1
	v_mfma_f32_16x16x32_bf16 v[62:65], v[150:153], v[204:207], v[62:65]
	v_mfma_f32_16x16x32_bf16 v[58:61], v[168:171], v[204:207], v[58:61]
	v_mfma_f32_16x16x32_bf16 v[46:49], v[150:153], v[214:217], v[46:49]
	v_mfma_f32_16x16x32_bf16 v[42:45], v[168:171], v[214:217], v[42:45]
	v_mfma_f32_16x16x32_bf16 v[30:33], v[150:153], v[222:225], v[30:33]
	v_mfma_f32_16x16x32_bf16 v[26:29], v[168:171], v[222:225], v[26:29]
	v_mfma_f32_16x16x32_bf16 v[14:17], v[150:153], v[230:233], v[14:17]
	v_mfma_f32_16x16x32_bf16 v[10:13], v[168:171], v[230:233], v[10:13]
	v_mfma_f32_16x16x32_bf16 v[62:65], v[164:167], v[210:213], v[62:65]
	v_mfma_f32_16x16x32_bf16 v[58:61], v[172:175], v[210:213], v[58:61]
	v_mfma_f32_16x16x32_bf16 v[46:49], v[164:167], v[218:221], v[46:49]
	v_mfma_f32_16x16x32_bf16 v[42:45], v[172:175], v[218:221], v[42:45]
	v_mfma_f32_16x16x32_bf16 v[30:33], v[164:167], v[226:229], v[30:33]
	v_mfma_f32_16x16x32_bf16 v[26:29], v[172:175], v[226:229], v[26:29]
	v_mfma_f32_16x16x32_bf16 v[14:17], v[164:167], v[234:237], v[14:17]
	v_mfma_f32_16x16x32_bf16 v[10:13], v[172:175], v[234:237], v[10:13]
	v_mfma_f32_16x16x32_bf16 v[54:57], v[180:183], v[204:207], v[54:57]
	v_mfma_f32_16x16x32_bf16 v[50:53], v[196:199], v[204:207], v[50:53]
	v_mfma_f32_16x16x32_bf16 v[38:41], v[180:183], v[214:217], v[38:41]
	v_mfma_f32_16x16x32_bf16 v[34:37], v[196:199], v[214:217], v[34:37]
	v_mfma_f32_16x16x32_bf16 v[22:25], v[180:183], v[222:225], v[22:25]
	v_mfma_f32_16x16x32_bf16 v[18:21], v[196:199], v[222:225], v[18:21]
	v_mfma_f32_16x16x32_bf16 v[6:9], v[180:183], v[230:233], v[6:9]
	v_mfma_f32_16x16x32_bf16 v[2:5], v[196:199], v[230:233], v[2:5]
	v_mfma_f32_16x16x32_bf16 v[54:57], v[184:187], v[210:213], v[54:57]
	v_mfma_f32_16x16x32_bf16 v[50:53], v[200:203], v[210:213], v[50:53]
	v_mfma_f32_16x16x32_bf16 v[38:41], v[184:187], v[218:221], v[38:41]
	v_mfma_f32_16x16x32_bf16 v[34:37], v[200:203], v[218:221], v[34:37]
	v_mfma_f32_16x16x32_bf16 v[22:25], v[184:187], v[226:229], v[22:25]
	v_mfma_f32_16x16x32_bf16 v[18:21], v[200:203], v[226:229], v[18:21]
	v_mfma_f32_16x16x32_bf16 v[6:9], v[184:187], v[234:237], v[6:9]
	v_mfma_f32_16x16x32_bf16 v[2:5], v[200:203], v[234:237], v[2:5]
	s_setprio 0
	s_barrier
	s_add_i32 s41, s41, 2
	s_add_u32 s16, s16, 0x100
	s_addc_u32 s17, s17, 0
	s_add_u32 s39, s39, 0x100
	s_addc_u32 s40, s40, 0
	s_cmp_gt_u32 s41, 41
	s_cbranch_scc0 .LBB0_1652
	s_and_b64 vcc, exec, s[12:13]
	s_cbranch_vccz .LBB0_1655
	s_barrier

.LBB0_1682:
	v_add_u32_e32 v164, s42, v150
	v_add_u32_e32 v181, s43, v150
	s_add_u32 s26, s22, s24
	ds_read_b128 v[152:155], v164
	ds_read_b128 v[156:159], v164 offset:1024
	ds_read_b128 v[160:163], v164 offset:2048
	ds_read_b128 v[164:167], v164 offset:3072
	ds_read_b128 v[168:171], v181
	ds_read_b128 v[172:175], v181 offset:1024
	ds_read_b128 v[176:179], v181 offset:2048
	ds_read_b128 v[182:185], v181 offset:3072
	s_addc_u32 s27, s23, s25
	s_add_u32 s26, s26, 0x100
	s_addc_u32 s27, s27, 0
	s_add_u32 s55, s19, s24
	s_addc_u32 s56, s49, s25
	s_cmpk_eq_i32 s24, 0x1500
	s_cselect_b32 s29, s7, s27
	s_cselect_b32 s28, s6, s26
	s_cselect_b32 s27, s21, s56
	s_cselect_b32 s26, s20, s55
	v_lshl_add_u64 v[208:209], v[146:147], 0, s[24:25]
	s_add_i32 m0, s35, 0xc000
	ds_read_b128 v[186:189], v151
	ds_read_b128 v[196:199], v151 offset:1024
	ds_read_b128 v[200:203], v151 offset:2048
	ds_read_b128 v[204:207], v151 offset:3072
	ds_read_b128 v[210:213], v151 offset:4096
	ds_read_b128 v[214:217], v151 offset:5120
	ds_read_b128 v[218:221], v151 offset:6144
	ds_read_b128 v[222:225], v151 offset:7168
	global_load_lds_dwordx4 v[208:209], off
	v_lshl_add_u64 v[208:209], v[148:149], 0, s[24:25]
	s_add_i32 m0, s35, 0xe000
	s_nop 0
	global_load_lds_dwordx4 v[208:209], off
	s_waitcnt vmcnt(8)
	s_waitcnt lgkmcnt(0)
	s_barrier
	s_setprio 1
	v_mfma_f32_16x16x32_bf16 v[142:145], v[152:155], v[186:189], v[142:145]
	v_mfma_f32_16x16x32_bf16 v[138:141], v[160:163], v[186:189], v[138:141]
	v_mfma_f32_16x16x32_bf16 v[126:129], v[152:155], v[200:203], v[126:129]
	v_mfma_f32_16x16x32_bf16 v[122:125], v[160:163], v[200:203], v[122:125]
	v_mfma_f32_16x16x32_bf16 v[110:113], v[152:155], v[210:213], v[110:113]
	v_mfma_f32_16x16x32_bf16 v[106:109], v[160:163], v[210:213], v[106:109]
	v_mfma_f32_16x16x32_bf16 v[94:97], v[152:155], v[218:221], v[94:97]
	v_mfma_f32_16x16x32_bf16 v[90:93], v[160:163], v[218:221], v[90:93]
	v_mfma_f32_16x16x32_bf16 v[142:145], v[156:159], v[196:199], v[142:145]
	v_mfma_f32_16x16x32_bf16 v[138:141], v[164:167], v[196:199], v[138:141]
	v_mfma_f32_16x16x32_bf16 v[126:129], v[156:159], v[204:207], v[126:129]
	v_mfma_f32_16x16x32_bf16 v[122:125], v[164:167], v[204:207], v[122:125]
	v_mfma_f32_16x16x32_bf16 v[110:113], v[156:159], v[214:217], v[110:113]
	v_mfma_f32_16x16x32_bf16 v[106:109], v[164:167], v[214:217], v[106:109]
	v_mfma_f32_16x16x32_bf16 v[94:97], v[156:159], v[222:225], v[94:97]
	v_mfma_f32_16x16x32_bf16 v[90:93], v[164:167], v[222:225], v[90:93]
	v_mfma_f32_16x16x32_bf16 v[134:137], v[168:171], v[186:189], v[134:137]
	v_mfma_f32_16x16x32_bf16 v[130:133], v[176:179], v[186:189], v[130:133]
	v_mfma_f32_16x16x32_bf16 v[118:121], v[168:171], v[200:203], v[118:121]
	v_mfma_f32_16x16x32_bf16 v[114:117], v[176:179], v[200:203], v[114:117]
	v_mfma_f32_16x16x32_bf16 v[102:105], v[168:171], v[210:213], v[102:105]
	v_mfma_f32_16x16x32_bf16 v[98:101], v[176:179], v[210:213], v[98:101]
	v_mfma_f32_16x16x32_bf16 v[86:89], v[168:171], v[218:221], v[86:89]
	v_mfma_f32_16x16x32_bf16 v[82:85], v[176:179], v[218:221], v[82:85]
	v_mfma_f32_16x16x32_bf16 v[134:137], v[172:175], v[196:199], v[134:137]
	v_mfma_f32_16x16x32_bf16 v[130:133], v[182:185], v[196:199], v[130:133]
	v_mfma_f32_16x16x32_bf16 v[118:121], v[172:175], v[204:207], v[118:121]
	v_mfma_f32_16x16x32_bf16 v[114:117], v[182:185], v[204:207], v[114:117]
	v_mfma_f32_16x16x32_bf16 v[102:105], v[172:175], v[214:217], v[102:105]
	v_mfma_f32_16x16x32_bf16 v[98:101], v[182:185], v[214:217], v[98:101]
	v_mfma_f32_16x16x32_bf16 v[86:89], v[172:175], v[222:225], v[86:89]
	v_mfma_f32_16x16x32_bf16 v[82:85], v[182:185], v[222:225], v[82:85]
	s_setprio 0
	s_barrier
	s_add_i32 s55, s42, s33
	v_lshl_add_u64 v[208:209], s[26:27], 0, v[4:5]
	s_mov_b32 m0, s55
	ds_read_b128 v[186:189], v151 offset:16384
	ds_read_b128 v[196:199], v151 offset:17408
	ds_read_b128 v[200:203], v151 offset:18432
	ds_read_b128 v[204:207], v151 offset:19456
	ds_read_b128 v[210:213], v151 offset:20480
	ds_read_b128 v[214:217], v151 offset:21504
	ds_read_b128 v[218:221], v151 offset:22528
	ds_read_b128 v[222:225], v151 offset:23552
	global_load_lds_dwordx4 v[208:209], off
	s_add_i32 m0, s55, 0x2000
	s_add_u32 s56, s26, 0xb0000
	v_lshl_add_u64 v[226:227], s[26:27], 0, v[8:9]
	s_addc_u32 s57, s27, 0
	s_add_i32 s55, s43, s33
	global_load_lds_dwordx4 v[226:227], off
	v_lshl_add_u64 v[228:229], s[56:57], 0, v[4:5]
	s_mov_b32 m0, s55
	v_lshl_add_u64 v[230:231], s[28:29], 0, v[6:7]
	global_load_lds_dwordx4 v[228:229], off
	v_lshl_add_u64 v[228:229], s[56:57], 0, v[8:9]
	s_add_i32 m0, s55, 0x2000
	s_nop 0
	global_load_lds_dwordx4 v[228:229], off
	v_lshl_add_u64 v[228:229], s[28:29], 0, v[2:3]
	s_mov_b32 m0, s35
	s_nop 0
	global_load_lds_dwordx4 v[228:229], off
	s_mov_b32 m0, s36
	s_nop 0
	global_load_lds_dwordx4 v[230:231], off
	s_waitcnt vmcnt(8)
	s_waitcnt lgkmcnt(0)
	s_barrier
	s_setprio 1
	v_mfma_f32_16x16x32_bf16 v[78:81], v[152:155], v[186:189], v[78:81]
	v_mfma_f32_16x16x32_bf16 v[74:77], v[160:163], v[186:189], v[74:77]
	v_mfma_f32_16x16x32_bf16 v[62:65], v[152:155], v[200:203], v[62:65]
	v_mfma_f32_16x16x32_bf16 v[58:61], v[160:163], v[200:203], v[58:61]
	v_mfma_f32_16x16x32_bf16 v[46:49], v[152:155], v[210:213], v[46:49]
	v_mfma_f32_16x16x32_bf16 v[42:45], v[160:163], v[210:213], v[42:45]
	v_mfma_f32_16x16x32_bf16 v[30:33], v[152:155], v[218:221], v[30:33]
	v_mfma_f32_16x16x32_bf16 v[26:29], v[160:163], v[218:221], v[26:29]
	v_mfma_f32_16x16x32_bf16 v[78:81], v[156:159], v[196:199], v[78:81]
	v_mfma_f32_16x16x32_bf16 v[74:77], v[164:167], v[196:199], v[74:77]
	v_mfma_f32_16x16x32_bf16 v[62:65], v[156:159], v[204:207], v[62:65]
	v_mfma_f32_16x16x32_bf16 v[58:61], v[164:167], v[204:207], v[58:61]
	v_mfma_f32_16x16x32_bf16 v[46:49], v[156:159], v[214:217], v[46:49]
	v_mfma_f32_16x16x32_bf16 v[42:45], v[164:167], v[214:217], v[42:45]
	v_mfma_f32_16x16x32_bf16 v[30:33], v[156:159], v[222:225], v[30:33]
	v_mfma_f32_16x16x32_bf16 v[26:29], v[164:167], v[222:225], v[26:29]
	v_mfma_f32_16x16x32_bf16 v[70:73], v[168:171], v[186:189], v[70:73]
	v_mfma_f32_16x16x32_bf16 v[66:69], v[176:179], v[186:189], v[66:69]
	v_mfma_f32_16x16x32_bf16 v[54:57], v[168:171], v[200:203], v[54:57]
	v_mfma_f32_16x16x32_bf16 v[50:53], v[176:179], v[200:203], v[50:53]
	v_mfma_f32_16x16x32_bf16 v[38:41], v[168:171], v[210:213], v[38:41]
	v_mfma_f32_16x16x32_bf16 v[34:37], v[176:179], v[210:213], v[34:37]
	v_mfma_f32_16x16x32_bf16 v[22:25], v[168:171], v[218:221], v[22:25]
	v_mfma_f32_16x16x32_bf16 v[18:21], v[176:179], v[218:221], v[18:21]
	v_mfma_f32_16x16x32_bf16 v[70:73], v[172:175], v[196:199], v[70:73]
	v_mfma_f32_16x16x32_bf16 v[66:69], v[182:185], v[196:199], v[66:69]
	v_mfma_f32_16x16x32_bf16 v[54:57], v[172:175], v[204:207], v[54:57]
	v_mfma_f32_16x16x32_bf16 v[50:53], v[182:185], v[204:207], v[50:53]
	v_mfma_f32_16x16x32_bf16 v[38:41], v[172:175], v[214:217], v[38:41]
	v_mfma_f32_16x16x32_bf16 v[34:37], v[182:185], v[214:217], v[34:37]
	v_mfma_f32_16x16x32_bf16 v[22:25], v[172:175], v[222:225], v[22:25]
	v_mfma_f32_16x16x32_bf16 v[18:21], v[182:185], v[222:225], v[18:21]
	s_setprio 0
	s_barrier
	s_add_i32 s55, 0, 0x18000
	s_add_i32 s56, 0, 0x1c000
	v_add_u32_e32 v164, s55, v150
	v_add_u32_e32 v181, s56, v150
	ds_read_b128 v[152:155], v164
	ds_read_b128 v[156:159], v164 offset:1024
	ds_read_b128 v[160:163], v164 offset:2048
	ds_read_b128 v[164:167], v164 offset:3072
	ds_read_b128 v[168:171], v181
	ds_read_b128 v[172:175], v181 offset:1024
	ds_read_b128 v[176:179], v181 offset:2048
	ds_read_b128 v[182:185], v181 offset:3072
	s_add_u32 s28, s28, 0xb0000
	s_addc_u32 s29, s29, 0
	s_mov_b32 m0, s37
	v_lshl_add_u64 v[232:233], s[28:29], 0, v[2:3]
	ds_read_b128 v[186:189], v151 offset:32768
	ds_read_b128 v[196:199], v151 offset:33792
	ds_read_b128 v[200:203], v151 offset:34816
	ds_read_b128 v[204:207], v151 offset:35840
	ds_read_b128 v[210:213], v151 offset:36864
	ds_read_b128 v[214:217], v151 offset:37888
	ds_read_b128 v[218:221], v151 offset:38912
	ds_read_b128 v[222:225], v151 offset:39936
	global_load_lds_dwordx4 v[232:233], off
	v_lshl_add_u64 v[232:233], s[28:29], 0, v[6:7]
	s_mov_b32 m0, s38
	s_nop 0
	global_load_lds_dwordx4 v[232:233], off
	s_waitcnt vmcnt(8)
	s_waitcnt lgkmcnt(0)
	s_barrier
	s_setprio 1
	v_mfma_f32_16x16x32_bf16 v[142:145], v[152:155], v[186:189], v[142:145]
	v_mfma_f32_16x16x32_bf16 v[138:141], v[160:163], v[186:189], v[138:141]
	v_mfma_f32_16x16x32_bf16 v[126:129], v[152:155], v[200:203], v[126:129]
	v_mfma_f32_16x16x32_bf16 v[122:125], v[160:163], v[200:203], v[122:125]
	v_mfma_f32_16x16x32_bf16 v[110:113], v[152:155], v[210:213], v[110:113]
	v_mfma_f32_16x16x32_bf16 v[106:109], v[160:163], v[210:213], v[106:109]
	v_mfma_f32_16x16x32_bf16 v[94:97], v[152:155], v[218:221], v[94:97]
	v_mfma_f32_16x16x32_bf16 v[90:93], v[160:163], v[218:221], v[90:93]
	v_mfma_f32_16x16x32_bf16 v[142:145], v[156:159], v[196:199], v[142:145]
	v_mfma_f32_16x16x32_bf16 v[138:141], v[164:167], v[196:199], v[138:141]
	v_mfma_f32_16x16x32_bf16 v[126:129], v[156:159], v[204:207], v[126:129]
	v_mfma_f32_16x16x32_bf16 v[122:125], v[164:167], v[204:207], v[122:125]
	v_mfma_f32_16x16x32_bf16 v[110:113], v[156:159], v[214:217], v[110:113]
	v_mfma_f32_16x16x32_bf16 v[106:109], v[164:167], v[214:217], v[106:109]
	v_mfma_f32_16x16x32_bf16 v[94:97], v[156:159], v[222:225], v[94:97]
	v_mfma_f32_16x16x32_bf16 v[90:93], v[164:167], v[222:225], v[90:93]
	v_mfma_f32_16x16x32_bf16 v[134:137], v[168:171], v[186:189], v[134:137]
	v_mfma_f32_16x16x32_bf16 v[130:133], v[176:179], v[186:189], v[130:133]
	v_mfma_f32_16x16x32_bf16 v[118:121], v[168:171], v[200:203], v[118:121]
	v_mfma_f32_16x16x32_bf16 v[114:117], v[176:179], v[200:203], v[114:117]
	v_mfma_f32_16x16x32_bf16 v[102:105], v[168:171], v[210:213], v[102:105]
	v_mfma_f32_16x16x32_bf16 v[98:101], v[176:179], v[210:213], v[98:101]
	v_mfma_f32_16x16x32_bf16 v[86:89], v[168:171], v[218:221], v[86:89]
	v_mfma_f32_16x16x32_bf16 v[82:85], v[176:179], v[218:221], v[82:85]
	v_mfma_f32_16x16x32_bf16 v[134:137], v[172:175], v[196:199], v[134:137]
	v_mfma_f32_16x16x32_bf16 v[130:133], v[182:185], v[196:199], v[130:133]
	v_mfma_f32_16x16x32_bf16 v[118:121], v[172:175], v[204:207], v[118:121]
	v_mfma_f32_16x16x32_bf16 v[114:117], v[182:185], v[204:207], v[114:117]
	v_mfma_f32_16x16x32_bf16 v[102:105], v[172:175], v[214:217], v[102:105]
	v_mfma_f32_16x16x32_bf16 v[98:101], v[182:185], v[214:217], v[98:101]
	v_mfma_f32_16x16x32_bf16 v[86:89], v[172:175], v[222:225], v[86:89]
	v_mfma_f32_16x16x32_bf16 v[82:85], v[182:185], v[222:225], v[82:85]
	s_setprio 0
	s_barrier
	s_add_i32 s28, s55, s33
	v_lshl_add_u64 v[208:209], v[208:209], 0, s[14:15]
	s_mov_b32 m0, s28
	ds_read_b128 v[186:189], v151 offset:49152
	ds_read_b128 v[196:199], v151 offset:50176
	ds_read_b128 v[200:203], v151 offset:51200
	ds_read_b128 v[204:207], v151 offset:52224
	ds_read_b128 v[210:213], v151 offset:53248
	ds_read_b128 v[214:217], v151 offset:54272
	ds_read_b128 v[218:221], v151 offset:55296
	ds_read_b128 v[222:225], v151 offset:56320
	global_load_lds_dwordx4 v[208:209], off
	s_add_i32 m0, s28, 0x2000
	s_add_u32 s26, s26, 0xb0080
	v_lshl_add_u64 v[208:209], v[226:227], 0, s[14:15]
	s_addc_u32 s27, s27, 0
	s_add_i32 s28, s56, s33
	global_load_lds_dwordx4 v[208:209], off
	v_lshl_add_u64 v[208:209], s[26:27], 0, v[4:5]
	s_mov_b32 m0, s28
	s_nop 0
	global_load_lds_dwordx4 v[208:209], off
	v_lshl_add_u64 v[208:209], s[26:27], 0, v[8:9]
	s_add_i32 m0, s28, 0x2000
	s_nop 0
	global_load_lds_dwordx4 v[208:209], off
	v_lshl_add_u64 v[208:209], v[228:229], 0, s[14:15]
	s_mov_b32 m0, s40
	s_nop 0
	global_load_lds_dwordx4 v[208:209], off
	v_lshl_add_u64 v[208:209], v[230:231], 0, s[14:15]
	s_mov_b32 m0, s41
	s_nop 0
	global_load_lds_dwordx4 v[208:209], off
	s_waitcnt vmcnt(8)
	s_waitcnt lgkmcnt(0)
	s_barrier
	s_setprio 1
	v_mfma_f32_16x16x32_bf16 v[78:81], v[152:155], v[186:189], v[78:81]
	v_mfma_f32_16x16x32_bf16 v[74:77], v[160:163], v[186:189], v[74:77]
	v_mfma_f32_16x16x32_bf16 v[62:65], v[152:155], v[200:203], v[62:65]
	v_mfma_f32_16x16x32_bf16 v[58:61], v[160:163], v[200:203], v[58:61]
	v_mfma_f32_16x16x32_bf16 v[46:49], v[152:155], v[210:213], v[46:49]
	v_mfma_f32_16x16x32_bf16 v[42:45], v[160:163], v[210:213], v[42:45]
	v_mfma_f32_16x16x32_bf16 v[30:33], v[152:155], v[218:221], v[30:33]
	v_mfma_f32_16x16x32_bf16 v[26:29], v[160:163], v[218:221], v[26:29]
	v_mfma_f32_16x16x32_bf16 v[78:81], v[156:159], v[196:199], v[78:81]
	v_mfma_f32_16x16x32_bf16 v[74:77], v[164:167], v[196:199], v[74:77]
	v_mfma_f32_16x16x32_bf16 v[62:65], v[156:159], v[204:207], v[62:65]
	v_mfma_f32_16x16x32_bf16 v[58:61], v[164:167], v[204:207], v[58:61]
	v_mfma_f32_16x16x32_bf16 v[46:49], v[156:159], v[214:217], v[46:49]
	v_mfma_f32_16x16x32_bf16 v[42:45], v[164:167], v[214:217], v[42:45]
	v_mfma_f32_16x16x32_bf16 v[30:33], v[156:159], v[222:225], v[30:33]
	v_mfma_f32_16x16x32_bf16 v[26:29], v[164:167], v[222:225], v[26:29]
	v_mfma_f32_16x16x32_bf16 v[70:73], v[168:171], v[186:189], v[70:73]
	v_mfma_f32_16x16x32_bf16 v[66:69], v[176:179], v[186:189], v[66:69]
	v_mfma_f32_16x16x32_bf16 v[54:57], v[168:171], v[200:203], v[54:57]
	v_mfma_f32_16x16x32_bf16 v[50:53], v[176:179], v[200:203], v[50:53]
	v_mfma_f32_16x16x32_bf16 v[38:41], v[168:171], v[210:213], v[38:41]
	v_mfma_f32_16x16x32_bf16 v[34:37], v[176:179], v[210:213], v[34:37]
	v_mfma_f32_16x16x32_bf16 v[22:25], v[168:171], v[218:221], v[22:25]
	v_mfma_f32_16x16x32_bf16 v[18:21], v[176:179], v[218:221], v[18:21]
	v_mfma_f32_16x16x32_bf16 v[70:73], v[172:175], v[196:199], v[70:73]
	v_mfma_f32_16x16x32_bf16 v[66:69], v[182:185], v[196:199], v[66:69]
	v_mfma_f32_16x16x32_bf16 v[54:57], v[172:175], v[204:207], v[54:57]
	v_mfma_f32_16x16x32_bf16 v[50:53], v[182:185], v[204:207], v[50:53]
	v_mfma_f32_16x16x32_bf16 v[38:41], v[172:175], v[214:217], v[38:41]
	v_mfma_f32_16x16x32_bf16 v[34:37], v[182:185], v[214:217], v[34:37]
	v_mfma_f32_16x16x32_bf16 v[22:25], v[172:175], v[222:225], v[22:25]
	v_mfma_f32_16x16x32_bf16 v[18:21], v[182:185], v[222:225], v[18:21]
	s_setprio 0
	s_barrier
	s_add_i32 s54, s54, 2
	s_add_u32 s24, s24, 0x100
	s_addc_u32 s25, s25, 0
	s_cmp_gt_u32 s54, 41
	s_cbranch_scc0 .LBB0_1682
	s_and_b64 vcc, exec, s[16:17]
	s_cbranch_vccz .LBB0_1685
	s_barrier

.LBB0_1770:
	s_add_u32 s34, s20, s11
	s_addc_u32 s35, s21, 0
	s_add_u32 s28, s34, 0x100
	s_addc_u32 s29, s35, 0
	s_and_b64 s[26:27], s[24:25], exec
	s_cselect_b32 s29, s13, s29
	s_cselect_b32 s28, s12, s28
	s_add_u32 s11, s18, s11
	s_addc_u32 s26, s19, 0
	s_add_u32 s11, s11, 0x100
	s_addc_u32 s26, s26, 0
	s_and_b64 s[24:25], s[24:25], exec
	s_cselect_b32 s31, s15, s26
	s_cselect_b32 s30, s14, s11
	s_add_u32 s36, s34, 0xb0080
	ds_read_b128 v[150:153], v147
	ds_read_b128 v[154:157], v147 offset:1024
	ds_read_b128 v[158:161], v147 offset:2048
	ds_read_b128 v[162:165], v147 offset:3072
	ds_read_b128 v[166:169], v148
	ds_read_b128 v[170:173], v148 offset:1024
	ds_read_b128 v[174:177], v148 offset:2048
	ds_read_b128 v[178:181], v148 offset:3072
	s_addc_u32 s37, s35, 0
	s_add_i32 s66, s48, s33
	s_add_i32 s63, s66, 0x2000
	s_add_u32 s34, s30, 0xb0000
	s_addc_u32 s35, s31, 0
	s_add_i32 s65, s49, s33
	s_add_i32 s64, s65, 0x2000
	s_add_i32 s62, 0, 0x18000
	s_add_i32 s61, 0, 0x1c000
	s_add_u32 s26, s28, 0xb0000
	s_addc_u32 s27, s29, 0
	s_add_i32 s60, s62, s33
	s_add_i32 s11, s60, 0x2000
	s_add_u32 s24, s30, 0xb0080
	s_addc_u32 s25, s31, 0
	s_add_i32 s68, s61, s33
	s_add_i32 s67, s68, 0x2000
	s_mov_b32 m0, s54
	v_lshl_add_u64 v[142:143], s[36:37], 0, v[136:137]
	ds_read_b128 v[182:185], v149
	ds_read_b128 v[186:189], v149 offset:1024
	ds_read_b128 v[190:193], v149 offset:2048
	ds_read_b128 v[194:197], v149 offset:3072
	ds_read_b128 v[198:201], v149 offset:4096
	ds_read_b128 v[202:205], v149 offset:5120
	ds_read_b128 v[210:213], v149 offset:6144
	ds_read_b128 v[214:217], v149 offset:7168
	global_load_lds_dwordx4 v[142:143], off
	v_lshl_add_u64 v[142:143], s[36:37], 0, v[132:133]
	s_mov_b32 m0, s55
	s_nop 0
	global_load_lds_dwordx4 v[142:143], off
	s_waitcnt vmcnt(8)
	s_waitcnt lgkmcnt(0)
	s_barrier
	s_setprio 1
	v_mfma_f32_16x16x32_bf16 v[126:129], v[150:153], v[182:185], v[126:129]
	v_mfma_f32_16x16x32_bf16 v[122:125], v[158:161], v[182:185], v[122:125]
	v_mfma_f32_16x16x32_bf16 v[114:117], v[150:153], v[190:193], v[114:117]
	v_mfma_f32_16x16x32_bf16 v[106:109], v[158:161], v[190:193], v[106:109]
	v_mfma_f32_16x16x32_bf16 v[98:101], v[150:153], v[198:201], v[98:101]
	v_mfma_f32_16x16x32_bf16 v[90:93], v[158:161], v[198:201], v[90:93]
	v_mfma_f32_16x16x32_bf16 v[82:85], v[150:153], v[210:213], v[82:85]
	v_mfma_f32_16x16x32_bf16 v[74:77], v[158:161], v[210:213], v[74:77]
	v_mfma_f32_16x16x32_bf16 v[126:129], v[154:157], v[186:189], v[126:129]
	v_mfma_f32_16x16x32_bf16 v[122:125], v[162:165], v[186:189], v[122:125]
	v_mfma_f32_16x16x32_bf16 v[114:117], v[154:157], v[194:197], v[114:117]
	v_mfma_f32_16x16x32_bf16 v[106:109], v[162:165], v[194:197], v[106:109]
	v_mfma_f32_16x16x32_bf16 v[98:101], v[154:157], v[202:205], v[98:101]
	v_mfma_f32_16x16x32_bf16 v[90:93], v[162:165], v[202:205], v[90:93]
	v_mfma_f32_16x16x32_bf16 v[82:85], v[154:157], v[214:217], v[82:85]
	v_mfma_f32_16x16x32_bf16 v[74:77], v[162:165], v[214:217], v[74:77]
	v_mfma_f32_16x16x32_bf16 v[118:121], v[166:169], v[182:185], v[118:121]
	v_mfma_f32_16x16x32_bf16 v[110:113], v[174:177], v[182:185], v[110:113]
	v_mfma_f32_16x16x32_bf16 v[102:105], v[166:169], v[190:193], v[102:105]
	v_mfma_f32_16x16x32_bf16 v[94:97], v[174:177], v[190:193], v[94:97]
	v_mfma_f32_16x16x32_bf16 v[86:89], v[166:169], v[198:201], v[86:89]
	v_mfma_f32_16x16x32_bf16 v[78:81], v[174:177], v[198:201], v[78:81]
	v_mfma_f32_16x16x32_bf16 v[70:73], v[166:169], v[210:213], v[70:73]
	v_mfma_f32_16x16x32_bf16 v[66:69], v[174:177], v[210:213], v[66:69]
	v_mfma_f32_16x16x32_bf16 v[118:121], v[170:173], v[186:189], v[118:121]
	v_mfma_f32_16x16x32_bf16 v[110:113], v[178:181], v[186:189], v[110:113]
	v_mfma_f32_16x16x32_bf16 v[102:105], v[170:173], v[194:197], v[102:105]
	v_mfma_f32_16x16x32_bf16 v[94:97], v[178:181], v[194:197], v[94:97]
	v_mfma_f32_16x16x32_bf16 v[86:89], v[170:173], v[202:205], v[86:89]
	v_mfma_f32_16x16x32_bf16 v[78:81], v[178:181], v[202:205], v[78:81]
	v_mfma_f32_16x16x32_bf16 v[70:73], v[170:173], v[214:217], v[70:73]
	v_mfma_f32_16x16x32_bf16 v[66:69], v[178:181], v[214:217], v[66:69]
	s_setprio 0
	s_barrier
	s_mov_b32 m0, s66
	v_lshl_add_u64 v[142:143], s[30:31], 0, v[134:135]
	ds_read_b128 v[182:185], v149 offset:16384
	ds_read_b128 v[186:189], v149 offset:17408
	ds_read_b128 v[190:193], v149 offset:18432
	ds_read_b128 v[194:197], v149 offset:19456
	ds_read_b128 v[198:201], v149 offset:20480
	ds_read_b128 v[202:205], v149 offset:21504
	ds_read_b128 v[210:213], v149 offset:22528
	ds_read_b128 v[214:217], v149 offset:23552
	global_load_lds_dwordx4 v[142:143], off
	v_lshl_add_u64 v[206:207], s[30:31], 0, v[130:131]
	s_mov_b32 m0, s63
	v_lshl_add_u64 v[208:209], s[34:35], 0, v[134:135]
	global_load_lds_dwordx4 v[206:207], off
	s_mov_b32 m0, s65
	v_lshl_add_u64 v[218:219], s[28:29], 0, v[132:133]
	global_load_lds_dwordx4 v[208:209], off
	v_lshl_add_u64 v[208:209], s[34:35], 0, v[130:131]
	s_mov_b32 m0, s64
	s_nop 0
	global_load_lds_dwordx4 v[208:209], off
	v_lshl_add_u64 v[208:209], s[28:29], 0, v[136:137]
	s_mov_b32 m0, s17
	s_nop 0
	global_load_lds_dwordx4 v[208:209], off
	s_mov_b32 m0, s38
	s_nop 0
	global_load_lds_dwordx4 v[218:219], off
	s_waitcnt vmcnt(8)
	s_waitcnt lgkmcnt(0)
	s_barrier
	s_setprio 1
	v_mfma_f32_16x16x32_bf16 v[62:65], v[150:153], v[182:185], v[62:65]
	v_mfma_f32_16x16x32_bf16 v[58:61], v[158:161], v[182:185], v[58:61]
	v_mfma_f32_16x16x32_bf16 v[50:53], v[150:153], v[190:193], v[50:53]
	v_mfma_f32_16x16x32_bf16 v[42:45], v[158:161], v[190:193], v[42:45]
	v_mfma_f32_16x16x32_bf16 v[34:37], v[150:153], v[198:201], v[34:37]
	v_mfma_f32_16x16x32_bf16 v[26:29], v[158:161], v[198:201], v[26:29]
	v_mfma_f32_16x16x32_bf16 v[18:21], v[150:153], v[210:213], v[18:21]
	v_mfma_f32_16x16x32_bf16 v[10:13], v[158:161], v[210:213], v[10:13]
	v_mfma_f32_16x16x32_bf16 v[62:65], v[154:157], v[186:189], v[62:65]
	v_mfma_f32_16x16x32_bf16 v[58:61], v[162:165], v[186:189], v[58:61]
	v_mfma_f32_16x16x32_bf16 v[50:53], v[154:157], v[194:197], v[50:53]
	v_mfma_f32_16x16x32_bf16 v[42:45], v[162:165], v[194:197], v[42:45]
	v_mfma_f32_16x16x32_bf16 v[34:37], v[154:157], v[202:205], v[34:37]
	v_mfma_f32_16x16x32_bf16 v[26:29], v[162:165], v[202:205], v[26:29]
	v_mfma_f32_16x16x32_bf16 v[18:21], v[154:157], v[214:217], v[18:21]
	v_mfma_f32_16x16x32_bf16 v[10:13], v[162:165], v[214:217], v[10:13]
	v_mfma_f32_16x16x32_bf16 v[54:57], v[166:169], v[182:185], v[54:57]
	v_mfma_f32_16x16x32_bf16 v[46:49], v[174:177], v[182:185], v[46:49]
	v_mfma_f32_16x16x32_bf16 v[38:41], v[166:169], v[190:193], v[38:41]
	v_mfma_f32_16x16x32_bf16 v[30:33], v[174:177], v[190:193], v[30:33]
	v_mfma_f32_16x16x32_bf16 v[22:25], v[166:169], v[198:201], v[22:25]
	v_mfma_f32_16x16x32_bf16 v[14:17], v[174:177], v[198:201], v[14:17]
	v_mfma_f32_16x16x32_bf16 v[6:9], v[166:169], v[210:213], v[6:9]
	v_mfma_f32_16x16x32_bf16 v[2:5], v[174:177], v[210:213], v[2:5]
	v_mfma_f32_16x16x32_bf16 v[54:57], v[170:173], v[186:189], v[54:57]
	v_mfma_f32_16x16x32_bf16 v[46:49], v[178:181], v[186:189], v[46:49]
	v_mfma_f32_16x16x32_bf16 v[38:41], v[170:173], v[194:197], v[38:41]
	v_mfma_f32_16x16x32_bf16 v[30:33], v[178:181], v[194:197], v[30:33]
	v_mfma_f32_16x16x32_bf16 v[22:25], v[170:173], v[202:205], v[22:25]
	v_mfma_f32_16x16x32_bf16 v[14:17], v[178:181], v[202:205], v[14:17]
	v_mfma_f32_16x16x32_bf16 v[6:9], v[170:173], v[214:217], v[6:9]
	v_mfma_f32_16x16x32_bf16 v[2:5], v[178:181], v[214:217], v[2:5]
	s_setprio 0
	s_barrier
	v_add_u32_e32 v139, s62, v145
	ds_read_b128 v[150:153], v139
	ds_read_b128 v[154:157], v139 offset:1024
	ds_read_b128 v[158:161], v139 offset:2048
	ds_read_b128 v[162:165], v139 offset:3072
	v_add_u32_e32 v139, s61, v145
	ds_read_b128 v[166:169], v139
	ds_read_b128 v[170:173], v139 offset:1024
	ds_read_b128 v[174:177], v139 offset:2048
	ds_read_b128 v[178:181], v139 offset:3072
	s_mov_b32 m0, s39
	v_lshl_add_u64 v[220:221], s[26:27], 0, v[136:137]
	ds_read_b128 v[182:185], v149 offset:32768
	ds_read_b128 v[186:189], v149 offset:33792
	ds_read_b128 v[190:193], v149 offset:34816
	ds_read_b128 v[194:197], v149 offset:35840
	ds_read_b128 v[198:201], v149 offset:36864
	ds_read_b128 v[202:205], v149 offset:37888
	ds_read_b128 v[210:213], v149 offset:38912
	ds_read_b128 v[214:217], v149 offset:39936
	global_load_lds_dwordx4 v[220:221], off
	v_lshl_add_u64 v[220:221], s[26:27], 0, v[132:133]
	s_mov_b32 m0, s40
	s_nop 0
	global_load_lds_dwordx4 v[220:221], off
	s_waitcnt vmcnt(8)
	s_waitcnt lgkmcnt(0)
	s_barrier
	s_setprio 1
	v_mfma_f32_16x16x32_bf16 v[126:129], v[150:153], v[182:185], v[126:129]
	v_mfma_f32_16x16x32_bf16 v[122:125], v[158:161], v[182:185], v[122:125]
	v_mfma_f32_16x16x32_bf16 v[114:117], v[150:153], v[190:193], v[114:117]
	v_mfma_f32_16x16x32_bf16 v[106:109], v[158:161], v[190:193], v[106:109]
	v_mfma_f32_16x16x32_bf16 v[98:101], v[150:153], v[198:201], v[98:101]
	v_mfma_f32_16x16x32_bf16 v[90:93], v[158:161], v[198:201], v[90:93]
	v_mfma_f32_16x16x32_bf16 v[82:85], v[150:153], v[210:213], v[82:85]
	v_mfma_f32_16x16x32_bf16 v[74:77], v[158:161], v[210:213], v[74:77]
	v_mfma_f32_16x16x32_bf16 v[126:129], v[154:157], v[186:189], v[126:129]
	v_mfma_f32_16x16x32_bf16 v[122:125], v[162:165], v[186:189], v[122:125]
	v_mfma_f32_16x16x32_bf16 v[114:117], v[154:157], v[194:197], v[114:117]
	v_mfma_f32_16x16x32_bf16 v[106:109], v[162:165], v[194:197], v[106:109]
	v_mfma_f32_16x16x32_bf16 v[98:101], v[154:157], v[202:205], v[98:101]
	v_mfma_f32_16x16x32_bf16 v[90:93], v[162:165], v[202:205], v[90:93]
	v_mfma_f32_16x16x32_bf16 v[82:85], v[154:157], v[214:217], v[82:85]
	v_mfma_f32_16x16x32_bf16 v[74:77], v[162:165], v[214:217], v[74:77]
	v_mfma_f32_16x16x32_bf16 v[118:121], v[166:169], v[182:185], v[118:121]
	v_mfma_f32_16x16x32_bf16 v[110:113], v[174:177], v[182:185], v[110:113]
	v_mfma_f32_16x16x32_bf16 v[102:105], v[166:169], v[190:193], v[102:105]
	v_mfma_f32_16x16x32_bf16 v[94:97], v[174:177], v[190:193], v[94:97]
	v_mfma_f32_16x16x32_bf16 v[86:89], v[166:169], v[198:201], v[86:89]
	v_mfma_f32_16x16x32_bf16 v[78:81], v[174:177], v[198:201], v[78:81]
	v_mfma_f32_16x16x32_bf16 v[70:73], v[166:169], v[210:213], v[70:73]
	v_mfma_f32_16x16x32_bf16 v[66:69], v[174:177], v[210:213], v[66:69]
	v_mfma_f32_16x16x32_bf16 v[118:121], v[170:173], v[186:189], v[118:121]
	v_mfma_f32_16x16x32_bf16 v[110:113], v[178:181], v[186:189], v[110:113]
	v_mfma_f32_16x16x32_bf16 v[102:105], v[170:173], v[194:197], v[102:105]
	v_mfma_f32_16x16x32_bf16 v[94:97], v[178:181], v[194:197], v[94:97]
	v_mfma_f32_16x16x32_bf16 v[86:89], v[170:173], v[202:205], v[86:89]
	v_mfma_f32_16x16x32_bf16 v[78:81], v[178:181], v[202:205], v[78:81]
	v_mfma_f32_16x16x32_bf16 v[70:73], v[170:173], v[214:217], v[70:73]
	v_mfma_f32_16x16x32_bf16 v[66:69], v[178:181], v[214:217], v[66:69]
	s_setprio 0
	s_barrier
	s_mov_b32 m0, s60
	v_lshl_add_u64 v[142:143], v[142:143], 0, s[6:7]
	ds_read_b128 v[182:185], v149 offset:49152
	ds_read_b128 v[186:189], v149 offset:50176
	ds_read_b128 v[190:193], v149 offset:51200
	ds_read_b128 v[194:197], v149 offset:52224
	ds_read_b128 v[198:201], v149 offset:53248
	ds_read_b128 v[202:205], v149 offset:54272
	ds_read_b128 v[210:213], v149 offset:55296
	ds_read_b128 v[214:217], v149 offset:56320
	global_load_lds_dwordx4 v[142:143], off
	v_lshl_add_u64 v[142:143], v[206:207], 0, s[6:7]
	s_mov_b32 m0, s11
	s_nop 0
	global_load_lds_dwordx4 v[142:143], off
	v_lshl_add_u64 v[142:143], s[24:25], 0, v[134:135]
	s_mov_b32 m0, s68
	s_nop 0
	global_load_lds_dwordx4 v[142:143], off
	v_lshl_add_u64 v[142:143], s[24:25], 0, v[130:131]
	s_mov_b32 m0, s67
	s_nop 0
	global_load_lds_dwordx4 v[142:143], off
	v_lshl_add_u64 v[142:143], v[208:209], 0, s[6:7]
	s_mov_b32 m0, s44
	s_nop 0
	global_load_lds_dwordx4 v[142:143], off
	v_lshl_add_u64 v[142:143], v[218:219], 0, s[6:7]
	s_mov_b32 m0, s45
	s_nop 0
	global_load_lds_dwordx4 v[142:143], off
	s_waitcnt vmcnt(8)
	s_waitcnt lgkmcnt(0)
	s_barrier
	s_setprio 1
	v_mfma_f32_16x16x32_bf16 v[62:65], v[150:153], v[182:185], v[62:65]
	v_mfma_f32_16x16x32_bf16 v[58:61], v[158:161], v[182:185], v[58:61]
	v_mfma_f32_16x16x32_bf16 v[50:53], v[150:153], v[190:193], v[50:53]
	v_mfma_f32_16x16x32_bf16 v[42:45], v[158:161], v[190:193], v[42:45]
	v_mfma_f32_16x16x32_bf16 v[34:37], v[150:153], v[198:201], v[34:37]
	v_mfma_f32_16x16x32_bf16 v[26:29], v[158:161], v[198:201], v[26:29]
	v_mfma_f32_16x16x32_bf16 v[18:21], v[150:153], v[210:213], v[18:21]
	v_mfma_f32_16x16x32_bf16 v[10:13], v[158:161], v[210:213], v[10:13]
	v_mfma_f32_16x16x32_bf16 v[62:65], v[154:157], v[186:189], v[62:65]
	v_mfma_f32_16x16x32_bf16 v[58:61], v[162:165], v[186:189], v[58:61]
	v_mfma_f32_16x16x32_bf16 v[50:53], v[154:157], v[194:197], v[50:53]
	v_mfma_f32_16x16x32_bf16 v[42:45], v[162:165], v[194:197], v[42:45]
	v_mfma_f32_16x16x32_bf16 v[34:37], v[154:157], v[202:205], v[34:37]
	v_mfma_f32_16x16x32_bf16 v[26:29], v[162:165], v[202:205], v[26:29]
	v_mfma_f32_16x16x32_bf16 v[18:21], v[154:157], v[214:217], v[18:21]
	v_mfma_f32_16x16x32_bf16 v[10:13], v[162:165], v[214:217], v[10:13]
	v_mfma_f32_16x16x32_bf16 v[54:57], v[166:169], v[182:185], v[54:57]
	v_mfma_f32_16x16x32_bf16 v[46:49], v[174:177], v[182:185], v[46:49]
	v_mfma_f32_16x16x32_bf16 v[38:41], v[166:169], v[190:193], v[38:41]
	v_mfma_f32_16x16x32_bf16 v[30:33], v[174:177], v[190:193], v[30:33]
	v_mfma_f32_16x16x32_bf16 v[22:25], v[166:169], v[198:201], v[22:25]
	v_mfma_f32_16x16x32_bf16 v[14:17], v[174:177], v[198:201], v[14:17]
	v_mfma_f32_16x16x32_bf16 v[6:9], v[166:169], v[210:213], v[6:9]
	v_mfma_f32_16x16x32_bf16 v[2:5], v[174:177], v[210:213], v[2:5]
	v_mfma_f32_16x16x32_bf16 v[54:57], v[170:173], v[186:189], v[54:57]
	v_mfma_f32_16x16x32_bf16 v[46:49], v[178:181], v[186:189], v[46:49]
	v_mfma_f32_16x16x32_bf16 v[38:41], v[170:173], v[194:197], v[38:41]
	v_mfma_f32_16x16x32_bf16 v[30:33], v[178:181], v[194:197], v[30:33]
	v_mfma_f32_16x16x32_bf16 v[22:25], v[170:173], v[202:205], v[22:25]
	v_mfma_f32_16x16x32_bf16 v[14:17], v[178:181], v[202:205], v[14:17]
	v_mfma_f32_16x16x32_bf16 v[6:9], v[170:173], v[214:217], v[6:9]
	v_mfma_f32_16x16x32_bf16 v[2:5], v[178:181], v[214:217], v[2:5]
	s_setprio 0
	s_barrier
	s_movk_i32 s11, 0x100
	s_andn2_b64 vcc, exec, s[22:23]
	s_mov_b64 s[24:25], -1
	s_mov_b64 s[22:23], 0
	s_cbranch_vccz .LBB0_1770
	s_and_b64 vcc, exec, s[8:9]
	s_cbranch_vccz .LBB0_1773
	s_barrier
